# compressed branch: far-group C tuple set once per quad, unowed nop pad before the gate multiply removed
# speedup vs baseline: 1.0026x; 1.0026x over previous
; #define LAS __attribute__((address_space(3)))
; __device__ __forceinline__ void nsa_quad_pre(int bg, int quad, const bf16_t* Q, const bf16_t* KV, const bf16_t* KCMP, const bf16_t* VCMPT, const float* GN, bf16_t* ONSA, ...
;     const int r16 = lane & 15, q4 = lane >> 4, b = bg >> 2, g = bg & 3, t0 = quad * 4;
;     const unsigned koff = (unsigned)(r16 * 64 + q4 * 8) * 2u, voffS = (unsigned)(r16 * SEQ + q4 * 8) * 2u, voffC = (unsigned)(r16 * 512 + q4 * 8) * 2u;
;     const char* KWb = (const char*)(KV + 4 * (size_t)MTOK * 256 + (size_t)bg * SEQ * 64); const char* VWb = (const char*)(KV + 5 * (size_t)MTOK * 256 + (size_t)bg * 64 * SEQ);
;     const char* KCb = (const char*)(KCMP + (size_t)bg * 512 * 64); const char* VCb = (const char*)(VCMPT + (size_t)bg * 64 * 512);
;     ...
;     const size_t qoff = (size_t)(b * SEQ + t0 + (r16 & 3)) * 1024 + (g * 4 + (r16 >> 2)) * 64 + q4 * 8;
;     { const bf16x8 a0 = *(const bf16x8*)(Q + qoff), a1 = *(const bf16x8*)(Q + qoff + 32); *(LAS bf16x8*)(qfw + lane * 8) = a0; *(LAS bf16x8*)(qfw + 512 + lane * 8) = a1; }
;     const LAS bf16_t* qf = qfw + lane * 8;
;     const LAS float* bt = btab + q4 * 1028;
;     const f32x4 z4 = {0.f, 0.f, 0.f, 0.f};
;     KFrag KF; VFrag VF; f32x4 sc[4];
;     const int w_lo = (t0 - 511 > 0 ? t0 - 511 : 0) >> 6, w_hi = t0 >> 6;
;     f32x4 oc[4] = {z4, z4, z4, z4};
;     const int tl = t0 + 3, nvmax = tl >= 31 ? ((tl - 31) >> 4) + 1 : 0, ngr = (nvmax + 63) >> 6;
;     if (ngr > 0) {
;         float ls[4] = {0.f, 0.f, 0.f, 0.f};
;         load_k(KF, KP_C(0));
; __device__ __forceinline__ void nsa_phase(LAS unsigned char* lds, const bf16_t* Q, const bf16_t* KV, const bf16_t* KCMP, const bf16_t* VCMPT, const float* GN, const float* rel_bias, bf16_t* ONSA,
;                                           int tid, int lane, int wave) {
;     ...
;                 const int qb = (kk & 1) ? (32 * kk + 31 - idx) : (32 * kk + idx);
;                 nsa_quad_pre(bg, qb * 16 + wave * 2, Q, KV, KCMP, VCMPT, GN, ONSA, btab, Pb, psum, selall + (wave * 2) * 64, qfw, lane);
;                 nsa_quad_pre(bg, qb * 16 + wave * 2 + 1, Q, KV, KCMP, VCMPT, GN, ONSA, btab, Pb, psum, selall + (wave * 2 + 1) * 64, qfw, lane);
.LBB0_738:
	s_lshl_b32 s1, s3, 5
	s_sub_i32 s14, s1, s91
	s_and_b32 s0, s3, 1
	s_add_i32 s14, s14, 31
	s_add_i32 s1, s1, s91
	s_cmp_eq_u32 s0, 0
	s_cselect_b32 s18, s1, s14
	v_and_b32_e32 v232, 15, v184
	v_lshrrev_b32_e32 v233, 4, v184
	v_and_b32_e32 v234, 3, v232
	v_lshrrev_b32_e32 v235, 2, v232
	v_mul_u32_u24_e32 v173, 0x1010, v235
	ds_read_b32 v225, v173 offset:4096
	v_mov_b32_e32 v252, 0xf149f2ca
	v_and_b32_e32 v253, 1, v235
	v_xor_b32_e32 v0, v233, v234
	v_lshlrev_b32_e32 v0, 4, v0
	v_lshl_add_u32 v0, v253, 6, v0
	v_lshl_add_u32 v98, v235, 3, v234
	v_lshl_add_u32 v176, v98, 7, v0
	s_lshl_b32 s33, s80, 7
	v_lshl_add_u32 v177, v232, 7, v0
	v_subrev_u32_e32 v177, s33, v177
	v_lshlrev_b32_e32 v98, 7, v253
	v_sub_u32_e32 v178, 64, v98
	v_lshrrev_b32_e32 v98, 3, v184
	v_and_b32_e32 v99, 7, v184
	s_lshr_b32 s0, s80, 3
	s_and_b32 s1, s0, 1
	s_lshl_b32 s1, s1, 2
	v_and_b32_e32 v253, 3, v98
	v_or_b32_e32 v253, s1, v253
	v_xor_b32_e32 v253, v99, v253
	v_add_u32_e32 v0, s80, v98
	v_lshlrev_b32_e32 v174, 7, v0
	v_lshl_add_u32 v174, v253, 4, v174
	v_xor_b32_e32 v253, v99, v98
	v_lshlrev_b32_e32 v175, 10, v0
	v_lshl_add_u32 v175, v253, 4, v175
	s_add_i32 s94, s33, 0xa040
	s_add_i32 s95, s33, 0x1dc40
	s_add_i32 s46, s33, 0x20200
	s_lshr_b32 s15, s97, 13
	s_lshl_b32 s15, s15, 2
	s_and_b32 s1, s88, 3
	s_or_b32 s15, s15, s1
	s_lshl_b32 s15, s15, 16
	s_add_u32 s68, s30, 0x38110000
	s_addc_u32 s69, s31, 0
	s_add_u32 s68, s68, s15
	s_addc_u32 s69, s69, 0
	s_add_u32 s70, s30, 0x38210000
	s_addc_u32 s71, s31, 0
	s_add_u32 s70, s70, s15
	s_addc_u32 s71, s71, 0
	s_lshl_b32 s74, s18, 2
	s_add_i32 s74, s74, 66
	s_lshr_b32 s74, s74, 6
	s_mov_b32 s75, 0
	v_lshlrev_b32_e32 v98, 7, v233
	v_sub_u32_e32 v172, v234, v98
	v_add_u32_e32 v172, 0xffffffe1, v172
	s_lshl_b32 s0, s80, 10
	s_add_i32 s0, s0, 56384
	v_lshlrev_b32_e32 v215, 11, v234
	v_lshl_add_u32 v215, v233, 5, v215
	v_add_u32_e32 v215, s0, v215
	s_mov_b32 s92, 0
	s_mov_b32 s93, 0
	s_lshl_b32 s0, s92, 13
	s_add_i32 s0, s0, s33
	s_add_i32 m0, s0, 16448
	s_lshl_b32 s1, s93, 13
	s_add_u32 s72, s68, s1
	s_addc_u32 s73, s69, 0
	global_load_lds_dwordx4 v174, s[72:73]
	s_cmp_eq_u32 s92, 1
	s_cselect_b32 s0, s95, s94
	s_cmp_eq_u32 s92, 2
	s_cselect_b32 m0, s46, s0
	s_lshl_b32 s1, s93, 7
	s_add_u32 s72, s70, s1
	s_addc_u32 s73, s71, 0
	global_load_lds_dwordx4 v175, s[72:73]
	s_add_i32 s93, s93, 1
	s_cmp_ge_i32 s93, s74
	s_cselect_b32 s93, 0, s93
	s_add_i32 s92, s92, 1
	s_cmp_eq_u32 s92, 3
	s_cselect_b32 s92, 0, s92
	s_lshl_b32 s0, s92, 13
	s_add_i32 s0, s0, s33
	s_add_i32 m0, s0, 16448
	s_lshl_b32 s1, s93, 13
	s_add_u32 s72, s68, s1
	s_addc_u32 s73, s69, 0
	global_load_lds_dwordx4 v174, s[72:73]
	s_cmp_eq_u32 s92, 1
	s_cselect_b32 s0, s95, s94
	s_cmp_eq_u32 s92, 2
	s_cselect_b32 m0, s46, s0
	s_lshl_b32 s1, s93, 7
	s_add_u32 s72, s70, s1
	s_addc_u32 s73, s71, 0
	global_load_lds_dwordx4 v175, s[72:73]
	s_add_i32 s93, s93, 1
	s_cmp_ge_i32 s93, s74
	s_cselect_b32 s93, 0, s93
	s_add_i32 s92, s92, 1
	s_cmp_eq_u32 s92, 3
	s_cselect_b32 s92, 0, s92
	s_lshl_b32 s0, s18, 6
	s_add_i32 s0, s0, s97
	s_add_i32 s0, s0, s80
	v_add_u32_e32 v253, s0, v234
	s_and_b32 s1, s88, 3
	s_lshl_b32 s1, s1, 2
	v_add_u32_e32 v98, s1, v235
	v_lshlrev_b32_e32 v98, 7, v98
	v_lshl_add_u32 v98, v253, 11, v98
	v_lshl_add_u32 v98, v233, 4, v98
	v_add_u32_e32 v99, 0x2000, v98
	s_add_u32 s72, s30, 0x29900000
	s_addc_u32 s73, s31, 0
	global_load_dwordx4 v[34:37], v98, s[72:73] offset:0
	global_load_dwordx4 v[38:41], v98, s[72:73] offset:64
	global_load_dwordx4 v[42:45], v99, s[72:73] offset:0
	global_load_dwordx4 v[46:49], v99, s[72:73] offset:64
	s_waitcnt lgkmcnt(0)
	s_lshl_b32 s47, s18, 6
	s_add_i32 s47, s47, s80
	v_and_b32_e32 v232, 15, v184
	v_and_b32_e32 v234, 3, v232
	v_lshrrev_b32_e32 v235, 2, v232
	s_add_i32 s0, s47, s97
	v_add_u32_e32 v253, s0, v234
	s_and_b32 s1, s88, 3
	s_lshl_b32 s1, s1, 2
	v_add_u32_e32 v0, s1, v235
	v_mul_u32_u24_e32 v99, 0xc0, v253
	v_mul_u32_u24_e32 v0, 12, v0
	v_add_u32_e32 v99, v99, v0
	s_add_u32 s72, s30, 0x38310000
	s_addc_u32 s73, s31, 0
	global_load_dword v227, v99, s[72:73]
	v_mov_b32_e32 v2, 0
	v_mov_b32_e32 v3, 0
	v_mov_b32_e32 v4, 0
	v_mov_b32_e32 v5, 0
	v_mov_b32_e32 v6, 0
	v_mov_b32_e32 v7, 0
	v_mov_b32_e32 v8, 0
	v_mov_b32_e32 v9, 0
	v_mov_b32_e32 v10, 0
	v_mov_b32_e32 v11, 0
	v_mov_b32_e32 v12, 0
	v_mov_b32_e32 v13, 0
	v_mov_b32_e32 v14, 0
	v_mov_b32_e32 v15, 0
	v_mov_b32_e32 v16, 0
	v_mov_b32_e32 v17, 0
	s_sub_i32 s0, s47, 28
	s_ashr_i32 s0, s0, 4
	s_add_i32 s0, s0, 64
	s_ashr_i32 s53, s0, 6
	s_cmp_gt_i32 s47, 27
	s_cselect_b32 s53, s53, 0
	s_sub_i32 s0, s47, 2063
	s_ashr_i32 s52, s0, 10
	s_add_i32 s52, s52, 1
	s_max_i32 s52, s52, 0
	s_min_i32 s52, s52, s53
	v_add_u32_e32 v99, s47, v172
	v_and_b32_e32 v98, 15, v184
	v_mov_b32_e32 v170, 0
	v_mov_b32_e32 v228, v225
	v_mov_b32_e32 v229, v225
	v_mov_b32_e32 v230, v225
	v_mov_b32_e32 v231, v225
	s_waitcnt vmcnt(0)
	s_barrier
	s_mov_b32 s57, 0
; #define LAS __attribute__((address_space(3)))
; __device__ __forceinline__ float ex2(float x) { return __builtin_amdgcn_exp2f(x); }
; __device__ __forceinline__ void cmp_sm1(const f32x4 (&sc)[4], int gr, int t0, const LAS float* bt, float (&ls)[4], int r16) {
; #pragma unroll
;     for (int cc = 0; cc < 4; ++cc) {
;         const int cend = (gr * 64 + cc * 16 + r16) * 16 + 31;
; #pragma unroll
;         for (int i = 0; i < 4; ++i) { const int dist = t0 + i - cend; ls[i] += dist >= 0 ? ex2(sc[cc][i] + bt[clampd(dist)]) : 0.f; }
;     }
; }
; __device__ __forceinline__ void nsa_quad_pre(int bg, int quad, const bf16_t* Q, const bf16_t* KV, const bf16_t* KCMP, const bf16_t* VCMPT, const float* GN, bf16_t* ONSA, ...
;     ...
;     if (ngr > 0) {
;         float ls[4] = {0.f, 0.f, 0.f, 0.f};
;         load_k(KF, KP_C(0));
;         for (int gr = 0; gr < ngr; ++gr) {
;             qk_scores(KF, qf, sc);
;             load_k(KF, KP_C(gr + 1 < ngr ? gr + 1 : 0));
;             cmp_sm1(sc, gr, t0, bt, ls, r16);
;         }
.Lcmp_top_q0p1:
	s_cmp_ge_i32 s57, s53
	s_cbranch_scc1 .Lcmp_skip_q0p1
	s_lshl_b32 s0, s75, 13
	s_add_i32 s0, s0, 16448
	v_add_u32_e32 v179, s0, v176
	v_add_u32_e32 v226, v179, v178
	ds_read_b128 v[50:53], v179 offset:0
	ds_read_b128 v[54:57], v226 offset:0
	ds_read_b128 v[58:61], v179 offset:512
	ds_read_b128 v[62:65], v226 offset:512
	ds_read_b128 v[66:69], v179 offset:4096
	ds_read_b128 v[70:73], v226 offset:4096
	ds_read_b128 v[74:77], v179 offset:4608
	ds_read_b128 v[78:81], v226 offset:4608
	s_lshl_b32 s0, s92, 13
	s_add_i32 s0, s0, s33
	s_add_i32 m0, s0, 16448
	s_lshl_b32 s1, s93, 13
	s_add_u32 s72, s68, s1
	s_addc_u32 s73, s69, 0
	global_load_lds_dwordx4 v174, s[72:73]
	s_cmp_eq_u32 s92, 1
	s_cselect_b32 s0, s95, s94
	s_cmp_eq_u32 s92, 2
	s_cselect_b32 m0, s46, s0
	s_lshl_b32 s1, s93, 7
	s_add_u32 s72, s70, s1
	s_addc_u32 s73, s71, 0
	global_load_lds_dwordx4 v175, s[72:73]
	s_add_i32 s93, s93, 1
	s_cmp_ge_i32 s93, s74
	s_cselect_b32 s93, 0, s93
	s_add_i32 s92, s92, 1
	s_cmp_eq_u32 s92, 3
	s_cselect_b32 s92, 0, s92
	s_cmp_lt_i32 s57, s52
	s_cbranch_scc0 .Lcmp_gen_q0p1
	s_waitcnt lgkmcnt(7)
	v_mfma_f32_16x16x32_bf16 v[18:21], v[50:53], v[34:37], v[228:231]
	s_waitcnt lgkmcnt(6)
	v_mfma_f32_16x16x32_bf16 v[18:21], v[54:57], v[38:41], v[18:21]
	s_waitcnt lgkmcnt(5)
	v_mfma_f32_16x16x32_bf16 v[22:25], v[58:61], v[34:37], v[228:231]
	s_waitcnt lgkmcnt(4)
	v_mfma_f32_16x16x32_bf16 v[22:25], v[62:65], v[38:41], v[22:25]
	s_waitcnt lgkmcnt(3)
	v_mfma_f32_16x16x32_bf16 v[26:29], v[66:69], v[34:37], v[228:231]
	s_waitcnt lgkmcnt(2)
	v_mfma_f32_16x16x32_bf16 v[26:29], v[70:73], v[38:41], v[26:29]
	s_waitcnt lgkmcnt(1)
	v_mfma_f32_16x16x32_bf16 v[30:33], v[74:77], v[34:37], v[228:231]
	s_waitcnt lgkmcnt(0)
	v_mfma_f32_16x16x32_bf16 v[30:33], v[78:81], v[38:41], v[30:33]
	v_exp_f32_e32 v18, v18
	v_exp_f32_e32 v19, v19
	v_exp_f32_e32 v20, v20
	v_exp_f32_e32 v21, v21
	v_exp_f32_e32 v22, v22
	v_exp_f32_e32 v23, v23
	v_exp_f32_e32 v24, v24
	v_exp_f32_e32 v25, v25
	v_exp_f32_e32 v26, v26
	v_exp_f32_e32 v27, v27
	v_exp_f32_e32 v28, v28
	v_exp_f32_e32 v29, v29
	v_exp_f32_e32 v30, v30
	v_exp_f32_e32 v31, v31
	v_exp_f32_e32 v32, v32
	v_exp_f32_e32 v33, v33
	v_add_f32_e32 v18, v18, v19
	v_add_f32_e32 v20, v20, v21
	v_add_f32_e32 v22, v22, v23
	v_add_f32_e32 v24, v24, v25
	v_add_f32_e32 v26, v26, v27
	v_add_f32_e32 v28, v28, v29
	v_add_f32_e32 v30, v30, v31
	v_add_f32_e32 v32, v32, v33
	v_add_f32_e32 v18, v18, v20
	v_add_f32_e32 v22, v22, v24
	v_add_f32_e32 v26, v26, v28
	v_add_f32_e32 v30, v30, v32
	v_add_f32_e32 v18, v18, v22
	v_add_f32_e32 v26, v26, v30
	v_add_f32_e32 v18, v18, v26
	v_add_f32_e32 v170, v170, v18
	s_branch .Lcmp_tail_q0p1

; #define LAS __attribute__((address_space(3)))
; __device__ __forceinline__ bf16_t tobf(float x) { return (bf16_t)pk2(x, 0.f); }
; __device__ __forceinline__ float ex2(float x) { return __builtin_amdgcn_exp2f(x); }
; __device__ __forceinline__ void cmp_sm2(const f32x4 (&sc)[4], int gr, int t0, const LAS float* bt, const float (&inv)[4], LAS bf16_t* Pb, LAS float* psum, int r16, int q4) {
; #pragma unroll
;     for (int cc = 0; cc < 4; ++cc) {
;         const int kk = gr * 64 + cc * 16 + r16, cend = kk * 16 + 31;
; #pragma unroll
;         for (int i = 0; i < 4; ++i) { const int dist = t0 + i - cend; float p = dist >= 0 ? ex2(sc[cc][i] + bt[clampd(dist)]) * inv[i] : 0.f;
;             Pb[(4 * q4 + i) * 72 + cc * 16 + r16] = tobf(p); p += __shfl_xor(p, 16); p += __shfl_xor(p, 32); if (q4 == 0) psum[i * 512 + kk] = p; }
;     }
; }
; __device__ __forceinline__ void nsa_quad_pre(int bg, int quad, const bf16_t* Q, const bf16_t* KV, const bf16_t* KCMP, const bf16_t* VCMPT, const float* GN, bf16_t* ONSA, ...
;     ...
;         for (int gr = 0; gr < ngr; ++gr) {
;             const bool more = gr + 1 < ngr;
;             qk_scores(KF, qf, sc);
;             if (more) load_k(KF, KP_C(gr + 1));
;             cmp_sm2(sc, gr, t0, bt, inv, Pb, psum, r16, q4);
;             pv_step(VF, oc, Pb, r16, q4);
;             if (more) load_v(VF, VP_C(gr + 1));
;         }
.Lcmp_top_q0p2:
	s_cmp_ge_i32 s57, s53
	s_cbranch_scc1 .Lcmp_skip_q0p2
	s_lshl_b32 s0, s75, 13
	s_add_i32 s0, s0, 16448
	v_add_u32_e32 v179, s0, v176
	v_add_u32_e32 v226, v179, v178
	ds_read_b128 v[50:53], v179 offset:0
	ds_read_b128 v[54:57], v226 offset:0
	ds_read_b128 v[58:61], v179 offset:512
	ds_read_b128 v[62:65], v226 offset:512
	ds_read_b128 v[66:69], v179 offset:4096
	ds_read_b128 v[70:73], v226 offset:4096
	ds_read_b128 v[74:77], v179 offset:4608
	ds_read_b128 v[78:81], v226 offset:4608
	s_lshl_b32 s0, s92, 13
	s_add_i32 s0, s0, s33
	s_add_i32 m0, s0, 16448
	s_lshl_b32 s1, s93, 13
	s_add_u32 s72, s68, s1
	s_addc_u32 s73, s69, 0
	global_load_lds_dwordx4 v174, s[72:73]
	s_cmp_eq_u32 s92, 1
	s_cselect_b32 s0, s95, s94
	s_cmp_eq_u32 s92, 2
	s_cselect_b32 m0, s46, s0
	s_lshl_b32 s1, s93, 7
	s_add_u32 s72, s70, s1
	s_addc_u32 s73, s71, 0
	global_load_lds_dwordx4 v175, s[72:73]
	s_add_i32 s93, s93, 1
	s_cmp_ge_i32 s93, s74
	s_cselect_b32 s93, 0, s93
	s_add_i32 s92, s92, 1
	s_cmp_eq_u32 s92, 3
	s_cselect_b32 s92, 0, s92
	s_cmp_lt_i32 s57, s52
	s_cbranch_scc0 .Lcmp_gen_q0p2
	s_waitcnt lgkmcnt(7)
	v_mfma_f32_16x16x32_bf16 v[18:21], v[50:53], v[34:37], v[228:231]
	s_waitcnt lgkmcnt(6)
	v_mfma_f32_16x16x32_bf16 v[18:21], v[54:57], v[38:41], v[18:21]
	s_waitcnt lgkmcnt(5)
	v_mfma_f32_16x16x32_bf16 v[22:25], v[58:61], v[34:37], v[228:231]
	s_waitcnt lgkmcnt(4)
	v_mfma_f32_16x16x32_bf16 v[22:25], v[62:65], v[38:41], v[22:25]
	s_waitcnt lgkmcnt(3)
	v_mfma_f32_16x16x32_bf16 v[26:29], v[66:69], v[34:37], v[228:231]
	s_waitcnt lgkmcnt(2)
	v_mfma_f32_16x16x32_bf16 v[26:29], v[70:73], v[38:41], v[26:29]
	s_waitcnt lgkmcnt(1)
	v_mfma_f32_16x16x32_bf16 v[30:33], v[74:77], v[34:37], v[228:231]
	s_waitcnt lgkmcnt(0)
	v_mfma_f32_16x16x32_bf16 v[30:33], v[78:81], v[38:41], v[30:33]
	s_cmp_eq_u32 s75, 1
	s_cselect_b32 s0, s95, s94
	s_cmp_eq_u32 s75, 2
	s_cselect_b32 s0, s46, s0
	v_add_u32_e32 v179, s0, v177
	v_add_u32_e32 v226, v179, v178
	ds_read_b128 v[82:85], v179 offset:0
	ds_read_b128 v[86:89], v226 offset:0
	ds_read_b128 v[90:93], v179 offset:2048
	ds_read_b128 v[94:97], v226 offset:2048
	ds_read_b128 v[236:239], v179 offset:4096
	ds_read_b128 v[240:243], v226 offset:4096
	ds_read_b128 v[244:247], v179 offset:6144
	ds_read_b128 v[248:251], v226 offset:6144
	v_exp_f32_e32 v18, v18
	v_exp_f32_e32 v19, v19
	v_exp_f32_e32 v20, v20
	v_exp_f32_e32 v21, v21
	v_exp_f32_e32 v22, v22
	v_exp_f32_e32 v23, v23
	v_exp_f32_e32 v24, v24
	v_exp_f32_e32 v25, v25
	v_exp_f32_e32 v26, v26
	v_exp_f32_e32 v27, v27
	v_exp_f32_e32 v28, v28
	v_exp_f32_e32 v29, v29
	v_exp_f32_e32 v30, v30
	v_exp_f32_e32 v31, v31
	v_exp_f32_e32 v32, v32
	v_exp_f32_e32 v33, v33
	v_mul_f32_e32 v18, v18, v171
	v_mul_f32_e32 v19, v19, v171
	v_mul_f32_e32 v20, v20, v171
	v_mul_f32_e32 v21, v21, v171
	v_mul_f32_e32 v22, v22, v171
	v_mul_f32_e32 v23, v23, v171
	v_mul_f32_e32 v24, v24, v171
	v_mul_f32_e32 v25, v25, v171
	v_mul_f32_e32 v26, v26, v171
	v_mul_f32_e32 v27, v27, v171
	v_mul_f32_e32 v28, v28, v171
	v_mul_f32_e32 v29, v29, v171
	v_mul_f32_e32 v30, v30, v171
	v_mul_f32_e32 v31, v31, v171
	v_mul_f32_e32 v32, v32, v171
	v_mul_f32_e32 v33, v33, v171
	v_add_f32_dpp v50, v18, v18 row_shr:4 row_mask:0xf bank_mask:0xf
	v_add_f32_dpp v51, v19, v19 row_shr:4 row_mask:0xf bank_mask:0xf
	v_add_f32_dpp v52, v20, v20 row_shr:4 row_mask:0xf bank_mask:0xf
	v_add_f32_dpp v53, v21, v21 row_shr:4 row_mask:0xf bank_mask:0xf
	v_add_f32_dpp v54, v22, v22 row_shr:4 row_mask:0xf bank_mask:0xf
	v_add_f32_dpp v55, v23, v23 row_shr:4 row_mask:0xf bank_mask:0xf
	v_add_f32_dpp v56, v24, v24 row_shr:4 row_mask:0xf bank_mask:0xf
	v_add_f32_dpp v57, v25, v25 row_shr:4 row_mask:0xf bank_mask:0xf
	v_add_f32_dpp v58, v26, v26 row_shr:4 row_mask:0xf bank_mask:0xf
	v_add_f32_dpp v59, v27, v27 row_shr:4 row_mask:0xf bank_mask:0xf
	v_add_f32_dpp v60, v28, v28 row_shr:4 row_mask:0xf bank_mask:0xf
	v_add_f32_dpp v61, v29, v29 row_shr:4 row_mask:0xf bank_mask:0xf
	v_add_f32_dpp v62, v30, v30 row_shr:4 row_mask:0xf bank_mask:0xf
	v_add_f32_dpp v63, v31, v31 row_shr:4 row_mask:0xf bank_mask:0xf
	v_add_f32_dpp v64, v32, v32 row_shr:4 row_mask:0xf bank_mask:0xf
	v_add_f32_dpp v65, v33, v33 row_shr:4 row_mask:0xf bank_mask:0xf
	v_add_f32_dpp v50, v50, v50 row_shr:8 row_mask:0xf bank_mask:0xf
	v_add_f32_dpp v51, v51, v51 row_shr:8 row_mask:0xf bank_mask:0xf
	v_add_f32_dpp v52, v52, v52 row_shr:8 row_mask:0xf bank_mask:0xf
	v_add_f32_dpp v53, v53, v53 row_shr:8 row_mask:0xf bank_mask:0xf
	v_add_f32_dpp v54, v54, v54 row_shr:8 row_mask:0xf bank_mask:0xf
	v_add_f32_dpp v55, v55, v55 row_shr:8 row_mask:0xf bank_mask:0xf
	v_add_f32_dpp v56, v56, v56 row_shr:8 row_mask:0xf bank_mask:0xf
	v_add_f32_dpp v57, v57, v57 row_shr:8 row_mask:0xf bank_mask:0xf
	v_add_f32_dpp v58, v58, v58 row_shr:8 row_mask:0xf bank_mask:0xf
	v_add_f32_dpp v59, v59, v59 row_shr:8 row_mask:0xf bank_mask:0xf
	v_add_f32_dpp v60, v60, v60 row_shr:8 row_mask:0xf bank_mask:0xf
	v_add_f32_dpp v61, v61, v61 row_shr:8 row_mask:0xf bank_mask:0xf
	v_add_f32_dpp v62, v62, v62 row_shr:8 row_mask:0xf bank_mask:0xf
	v_add_f32_dpp v63, v63, v63 row_shr:8 row_mask:0xf bank_mask:0xf
	v_add_f32_dpp v64, v64, v64 row_shr:8 row_mask:0xf bank_mask:0xf
	v_add_f32_dpp v65, v65, v65 row_shr:8 row_mask:0xf bank_mask:0xf
	s_lshl_b32 s0, s57, 8
	v_add_u32_e32 v232, s0, v215
	v_cmp_lt_u32_e32 vcc, 11, v98
	s_nop 0
	s_and_saveexec_b64 s[20:21], vcc
	ds_write_b128 v232, v[50:53] offset:0
	ds_write_b128 v232, v[54:57] offset:16
	ds_write_b128 v232, v[58:61] offset:128
	ds_write_b128 v232, v[62:65] offset:144
	s_or_b64 exec, exec, s[20:21]
	v_cvt_pk_bf16_f32 v216, v18, v19
	v_cvt_pk_bf16_f32 v217, v20, v21
	v_cvt_pk_bf16_f32 v218, v22, v23
	v_cvt_pk_bf16_f32 v219, v24, v25
	v_cvt_pk_bf16_f32 v220, v26, v27
	v_cvt_pk_bf16_f32 v221, v28, v29
	v_cvt_pk_bf16_f32 v222, v30, v31
	v_cvt_pk_bf16_f32 v223, v32, v33
	s_waitcnt lgkmcnt(11)
	v_mfma_f32_16x16x32_bf16 v[2:5], v[82:85], v[216:219], v[2:5]
	s_waitcnt lgkmcnt(10)
	v_mfma_f32_16x16x32_bf16 v[2:5], v[86:89], v[220:223], v[2:5]
	s_waitcnt lgkmcnt(9)
	v_mfma_f32_16x16x32_bf16 v[6:9], v[90:93], v[216:219], v[6:9]
	s_waitcnt lgkmcnt(8)
	v_mfma_f32_16x16x32_bf16 v[6:9], v[94:97], v[220:223], v[6:9]
	s_waitcnt lgkmcnt(7)
	v_mfma_f32_16x16x32_bf16 v[10:13], v[236:239], v[216:219], v[10:13]
	s_waitcnt lgkmcnt(6)
	v_mfma_f32_16x16x32_bf16 v[10:13], v[240:243], v[220:223], v[10:13]
	s_waitcnt lgkmcnt(5)
	v_mfma_f32_16x16x32_bf16 v[14:17], v[244:247], v[216:219], v[14:17]
	s_waitcnt lgkmcnt(4)
	v_mfma_f32_16x16x32_bf16 v[14:17], v[248:251], v[220:223], v[14:17]
	s_branch .Lcmp_tail_q0p2

; #define LAS __attribute__((address_space(3)))
; #define CBAR() asm volatile("" ::: "memory")
; __device__ __forceinline__ bf16_t tobf(float x) { return (bf16_t)pk2(x, 0.f); }
; __device__ __forceinline__ void nsa_quad_pre(int bg, int quad, const bf16_t* Q, const bf16_t* KV, const bf16_t* KCMP, const bf16_t* VCMPT, const float* GN, bf16_t* ONSA, ...
;     ...
;     for (int tt = 0; tt < 4; ++tt) {
;         const int tok = t0 + tt, cur = tok >> 6;
;         if (cur < 16) { if (lane < 16) selq[tt * 16 + lane] = lane; }
;         else {
;             unsigned k0 = 0u, k1 = 0u;
;             { const int j = lane; if (j >= 1 && j <= cur - 2) { const LAS float* ps = psum + tt * 512 + 4 * j - 1; const float v = ps[0] + ps[1] + ps[2] + ps[3] + ps[4]; k0 = (__builtin_bit_cast(unsigned, v) & ~127u) | (unsigned)(127 - j); } }
;             { const int j = lane + 64; if (j <= cur - 2) { const LAS float* ps = psum + tt * 512 + 4 * j - 1; const float v = ps[0] + ps[1] + ps[2] + ps[3] + ps[4]; k1 = (__builtin_bit_cast(unsigned, v) & ~127u) | (unsigned)(127 - j); } }
;             for (int it = 0; it < 13; ++it) {
;                 unsigned m = k0 > k1 ? k0 : k1;
; #pragma unroll
;                 for (int off = 32; off >= 1; off >>= 1) { const unsigned o = (unsigned)__shfl_xor((int)m, off); m = o > m ? o : m; }
;                 if (k0 == m) k0 = 0u; if (k1 == m) k1 = 0u;
;                 if (lane == 0) selq[tt * 16 + it] = 127 - (int)(m & 127u);
;             }
;             if (lane == 0) { selq[tt * 16 + 13] = 0; selq[tt * 16 + 14] = cur - 1; selq[tt * 16 + 15] = cur; }
;         }
;     }
;     CBAR();
; #pragma unroll
;     for (int tt = 0; tt < 4; ++tt) { const float gc = GN[(size_t)(b * SEQ + t0 + tt) * 48 + (g * 4 + q4) * 3];
;         bf16_t* op = ONSA + (size_t)(b * SEQ + t0 + tt) * 1024 + (g * 4 + q4) * 64 + r16;
; #pragma unroll
;         for (int nt = 0; nt < 4; ++nt) op[nt * 16] = tobf(gc * oc[nt][tt]); }
.Lcmp_tail_q0p2:
	s_add_i32 s75, s75, 1
	s_cmp_eq_u32 s75, 3
	s_cselect_b32 s75, 0, s75
	s_add_i32 s57, s57, 1
	s_cmp_lt_i32 s57, s74
	s_waitcnt vmcnt(2) lgkmcnt(0)
	s_barrier
	s_cbranch_scc1 .Lcmp_top_q0p2
	s_waitcnt lgkmcnt(0)
	v_and_b32_e32 v232, 15, v184
	v_lshrrev_b32_e32 v233, 4, v184
	v_and_b32_e32 v234, 3, v232
	v_lshrrev_b32_e32 v235, 2, v232
	s_add_i32 s0, s47, s97
	v_add_u32_e32 v253, s0, v234
	s_and_b32 s1, s88, 3
	s_lshl_b32 s1, s1, 2
	v_add_u32_e32 v0, s1, v235
	v_lshlrev_b32_e32 v98, 7, v0
	v_lshl_add_u32 v98, v253, 11, v98
	v_lshl_add_u32 v98, v233, 3, v98
	s_add_u32 s14, s30, 0xf900000
	s_addc_u32 s15, s31, 0
	s_waitcnt vmcnt(0)
	v_mul_f32_e32 v2, v2, v227
	v_mul_f32_e32 v3, v3, v227
	v_mul_f32_e32 v4, v4, v227
	v_mul_f32_e32 v5, v5, v227
	v_mul_f32_e32 v6, v6, v227
	v_mul_f32_e32 v7, v7, v227
	v_mul_f32_e32 v8, v8, v227
	v_mul_f32_e32 v9, v9, v227
	v_mul_f32_e32 v10, v10, v227
	v_mul_f32_e32 v11, v11, v227
	v_mul_f32_e32 v12, v12, v227
	v_mul_f32_e32 v13, v13, v227
	v_mul_f32_e32 v14, v14, v227
	v_mul_f32_e32 v15, v15, v227
	v_mul_f32_e32 v16, v16, v227
	v_mul_f32_e32 v17, v17, v227
	v_cvt_pk_bf16_f32 v216, v2, v3
	v_cvt_pk_bf16_f32 v217, v4, v5
	v_cvt_pk_bf16_f32 v218, v6, v7
	v_cvt_pk_bf16_f32 v219, v8, v9
	v_cvt_pk_bf16_f32 v220, v10, v11
	v_cvt_pk_bf16_f32 v221, v12, v13
	v_cvt_pk_bf16_f32 v222, v14, v15
	v_cvt_pk_bf16_f32 v223, v16, v17
	global_store_dwordx2 v98, v[216:217], s[14:15] offset:0
	global_store_dwordx2 v98, v[218:219], s[14:15] offset:32
	global_store_dwordx2 v98, v[220:221], s[14:15] offset:64
	global_store_dwordx2 v98, v[222:223], s[14:15] offset:96
	s_waitcnt lgkmcnt(0)
	s_cmp_gt_i32 s18, 15
	s_cbranch_scc0 .Ltopk_small_q0
	s_lshl_b32 s19, s80, 10
	s_add_i32 s19, s19, 56384
	v_lshlrev_b32_e32 v96, 4, v184
	v_add_u32_e32 v96, s19, v96
	v_add_u32_e32 v97, 0xfffffffc, v96
	v_sub_u32_e32 v94, 127, v184
	v_sub_u32_e32 v95, 63, v184
	s_mov_b32 s54, 0xffffff80
	s_add_i32 s21, s18, -2
	v_add_u32_e32 v236, 64, v184
	ds_read_b32 v86, v97 offset:0
	ds_read_b128 v[50:53], v96 offset:0
	ds_read_b32 v87, v97 offset:1024
	ds_read_b128 v[54:57], v96 offset:1024
	ds_read_b32 v88, v97 offset:2048
	ds_read_b128 v[58:61], v96 offset:2048
	ds_read_b32 v89, v97 offset:3072
	ds_read_b128 v[62:65], v96 offset:3072
	s_waitcnt lgkmcnt(6)
	v_add_f32_e32 v86, v86, v50
	v_add_f32_e32 v86, v86, v51
	v_add_f32_e32 v86, v86, v52
	v_add_f32_e32 v86, v86, v53
	v_and_or_b32 v18, v86, s54, v94
	s_waitcnt lgkmcnt(4)
	v_add_f32_e32 v87, v87, v54
	v_add_f32_e32 v87, v87, v55
	v_add_f32_e32 v87, v87, v56
	v_add_f32_e32 v87, v87, v57
	v_and_or_b32 v22, v87, s54, v95
	s_waitcnt lgkmcnt(2)
	v_add_f32_e32 v88, v88, v58
	v_add_f32_e32 v88, v88, v59
	v_add_f32_e32 v88, v88, v60
	v_add_f32_e32 v88, v88, v61
	v_and_or_b32 v19, v88, s54, v94
	s_waitcnt lgkmcnt(0)
	v_add_f32_e32 v89, v89, v62
	v_add_f32_e32 v89, v89, v63
	v_add_f32_e32 v89, v89, v64
	v_add_f32_e32 v89, v89, v65
	v_and_or_b32 v23, v89, s54, v95
	ds_read_b32 v90, v97 offset:4096
	ds_read_b128 v[66:69], v96 offset:4096
	ds_read_b32 v91, v97 offset:5120
	ds_read_b128 v[70:73], v96 offset:5120
	ds_read_b32 v92, v97 offset:6144
	ds_read_b128 v[74:77], v96 offset:6144
	ds_read_b32 v93, v97 offset:7168
	ds_read_b128 v[78:81], v96 offset:7168
	s_waitcnt lgkmcnt(6)
	v_add_f32_e32 v90, v90, v66
	v_add_f32_e32 v90, v90, v67
	v_add_f32_e32 v90, v90, v68
	v_add_f32_e32 v90, v90, v69
	v_and_or_b32 v20, v90, s54, v94
	s_waitcnt lgkmcnt(4)
	v_add_f32_e32 v91, v91, v70
	v_add_f32_e32 v91, v91, v71
	v_add_f32_e32 v91, v91, v72
	v_add_f32_e32 v91, v91, v73
	v_and_or_b32 v24, v91, s54, v95
	s_waitcnt lgkmcnt(2)
	v_add_f32_e32 v92, v92, v74
	v_add_f32_e32 v92, v92, v75
	v_add_f32_e32 v92, v92, v76
	v_add_f32_e32 v92, v92, v77
	v_and_or_b32 v21, v92, s54, v94
	s_waitcnt lgkmcnt(0)
	v_add_f32_e32 v93, v93, v78
	v_add_f32_e32 v93, v93, v79
	v_add_f32_e32 v93, v93, v80
	v_add_f32_e32 v93, v93, v81
	v_and_or_b32 v25, v93, s54, v95
	v_cmp_le_i32_e64 s[14:15], v184, s21
	v_cmp_lt_i32_e64 s[34:35], 0, v184
	s_nop 0
	s_and_b64 s[14:15], s[14:15], s[34:35]
	v_cmp_le_i32_e64 s[34:35], v236, s21
	v_cndmask_b32_e64 v18, 0, v18, s[14:15]
	s_nop 0
	v_cndmask_b32_e64 v22, 0, v22, s[34:35]
	v_mov_b32_e32 v82, 127
	v_cndmask_b32_e64 v19, 0, v19, s[14:15]
	v_cndmask_b32_e64 v23, 0, v23, s[34:35]
	v_mov_b32_e32 v83, 127
	v_cndmask_b32_e64 v20, 0, v20, s[14:15]
	v_cndmask_b32_e64 v24, 0, v24, s[34:35]
	v_mov_b32_e32 v84, 127
	v_cndmask_b32_e64 v21, 0, v21, s[14:15]
	v_cndmask_b32_e64 v25, 0, v25, s[34:35]
	v_mov_b32_e32 v85, 127
	v_max_u32_e32 v26, v18, v22
	v_max_u32_e32 v27, v19, v23
	v_max_u32_e32 v28, v20, v24
	v_max_u32_e32 v29, v21, v25
	v_max_u32_dpp v26, v26, v26 quad_perm:[1,0,3,2] row_mask:0xf bank_mask:0xf
	v_max_u32_dpp v27, v27, v27 quad_perm:[1,0,3,2] row_mask:0xf bank_mask:0xf
	v_max_u32_dpp v28, v28, v28 quad_perm:[1,0,3,2] row_mask:0xf bank_mask:0xf
	v_max_u32_dpp v29, v29, v29 quad_perm:[1,0,3,2] row_mask:0xf bank_mask:0xf
	v_max_u32_dpp v26, v26, v26 quad_perm:[2,3,0,1] row_mask:0xf bank_mask:0xf
	v_max_u32_dpp v27, v27, v27 quad_perm:[2,3,0,1] row_mask:0xf bank_mask:0xf
	v_max_u32_dpp v28, v28, v28 quad_perm:[2,3,0,1] row_mask:0xf bank_mask:0xf
	v_max_u32_dpp v29, v29, v29 quad_perm:[2,3,0,1] row_mask:0xf bank_mask:0xf
	v_max_u32_dpp v26, v26, v26 row_half_mirror row_mask:0xf bank_mask:0xf
	v_max_u32_dpp v27, v27, v27 row_half_mirror row_mask:0xf bank_mask:0xf
	v_max_u32_dpp v28, v28, v28 row_half_mirror row_mask:0xf bank_mask:0xf
	v_max_u32_dpp v29, v29, v29 row_half_mirror row_mask:0xf bank_mask:0xf
	v_max_u32_dpp v26, v26, v26 row_mirror row_mask:0xf bank_mask:0xf
	v_max_u32_dpp v27, v27, v27 row_mirror row_mask:0xf bank_mask:0xf
; __device__ __forceinline__ void nsa_quad_pre(int bg, int quad, const bf16_t* Q, const bf16_t* KV, const bf16_t* KCMP, const bf16_t* VCMPT, const float* GN, bf16_t* ONSA, ...
;     ...
;             for (int it = 0; it < 13; ++it) {
;                 unsigned m = k0 > k1 ? k0 : k1;
; #pragma unroll
;                 for (int off = 32; off >= 1; off >>= 1) { const unsigned o = (unsigned)__shfl_xor((int)m, off); m = o > m ? o : m; }
;                 if (k0 == m) k0 = 0u; if (k1 == m) k1 = 0u;
;                 if (lane == 0) selq[tt * 16 + it] = 127 - (int)(m & 127u);
;             }
	v_max_u32_dpp v28, v28, v28 row_mirror row_mask:0xf bank_mask:0xf
	v_max_u32_dpp v29, v29, v29 row_mirror row_mask:0xf bank_mask:0xf
	v_max_u32_dpp v26, v26, v26 row_bcast:15 row_mask:0xa bank_mask:0xf
	v_max_u32_dpp v27, v27, v27 row_bcast:15 row_mask:0xa bank_mask:0xf
	v_max_u32_dpp v28, v28, v28 row_bcast:15 row_mask:0xa bank_mask:0xf
	v_max_u32_dpp v29, v29, v29 row_bcast:15 row_mask:0xa bank_mask:0xf
	v_max_u32_dpp v26, v26, v26 row_bcast:31 row_mask:0xc bank_mask:0xf
	v_max_u32_dpp v27, v27, v27 row_bcast:31 row_mask:0xc bank_mask:0xf
	v_max_u32_dpp v28, v28, v28 row_bcast:31 row_mask:0xc bank_mask:0xf
	v_max_u32_dpp v29, v29, v29 row_bcast:31 row_mask:0xc bank_mask:0xf
	v_readlane_b32 s14, v26, 63
	v_readlane_b32 s15, v27, 63
	v_readlane_b32 s34, v28, 63
	v_readlane_b32 s35, v29, 63
	v_writelane_b32 v82, s14, 0
	v_writelane_b32 v83, s15, 0
	v_writelane_b32 v84, s34, 0
	v_writelane_b32 v85, s35, 0
	v_cmp_ne_u32_e64 s[42:43], s14, v18
	v_cmp_ne_u32_e64 s[66:67], s14, v22
	v_cmp_ne_u32_e64 s[0:1], s15, v19
	v_cmp_ne_u32_e32 vcc, s15, v23
	v_cndmask_b32_e64 v18, 0, v18, s[42:43]
	v_cndmask_b32_e64 v22, 0, v22, s[66:67]
	v_cndmask_b32_e64 v19, 0, v19, s[0:1]
	v_cndmask_b32_e32 v23, 0, v23, vcc
	v_cmp_ne_u32_e64 s[42:43], s34, v20
	v_cmp_ne_u32_e64 s[66:67], s34, v24
	v_cmp_ne_u32_e64 s[0:1], s35, v21
	v_cmp_ne_u32_e32 vcc, s35, v25
	v_cndmask_b32_e64 v20, 0, v20, s[42:43]
	v_cndmask_b32_e64 v24, 0, v24, s[66:67]
	v_cndmask_b32_e64 v21, 0, v21, s[0:1]
	v_cndmask_b32_e32 v25, 0, v25, vcc
	v_max_u32_e32 v26, v18, v22
	v_max_u32_e32 v27, v19, v23
	v_max_u32_e32 v28, v20, v24
	v_max_u32_e32 v29, v21, v25
	v_max_u32_dpp v26, v26, v26 quad_perm:[1,0,3,2] row_mask:0xf bank_mask:0xf
	v_max_u32_dpp v27, v27, v27 quad_perm:[1,0,3,2] row_mask:0xf bank_mask:0xf
	v_max_u32_dpp v28, v28, v28 quad_perm:[1,0,3,2] row_mask:0xf bank_mask:0xf
	v_max_u32_dpp v29, v29, v29 quad_perm:[1,0,3,2] row_mask:0xf bank_mask:0xf
	v_max_u32_dpp v26, v26, v26 quad_perm:[2,3,0,1] row_mask:0xf bank_mask:0xf
	v_max_u32_dpp v27, v27, v27 quad_perm:[2,3,0,1] row_mask:0xf bank_mask:0xf
	v_max_u32_dpp v28, v28, v28 quad_perm:[2,3,0,1] row_mask:0xf bank_mask:0xf
	v_max_u32_dpp v29, v29, v29 quad_perm:[2,3,0,1] row_mask:0xf bank_mask:0xf
	v_max_u32_dpp v26, v26, v26 row_half_mirror row_mask:0xf bank_mask:0xf
	v_max_u32_dpp v27, v27, v27 row_half_mirror row_mask:0xf bank_mask:0xf
	v_max_u32_dpp v28, v28, v28 row_half_mirror row_mask:0xf bank_mask:0xf
	v_max_u32_dpp v29, v29, v29 row_half_mirror row_mask:0xf bank_mask:0xf
	v_max_u32_dpp v26, v26, v26 row_mirror row_mask:0xf bank_mask:0xf
	v_max_u32_dpp v27, v27, v27 row_mirror row_mask:0xf bank_mask:0xf
	v_max_u32_dpp v28, v28, v28 row_mirror row_mask:0xf bank_mask:0xf
	v_max_u32_dpp v29, v29, v29 row_mirror row_mask:0xf bank_mask:0xf
	v_max_u32_dpp v26, v26, v26 row_bcast:15 row_mask:0xa bank_mask:0xf
	v_max_u32_dpp v27, v27, v27 row_bcast:15 row_mask:0xa bank_mask:0xf
	v_max_u32_dpp v28, v28, v28 row_bcast:15 row_mask:0xa bank_mask:0xf
	v_max_u32_dpp v29, v29, v29 row_bcast:15 row_mask:0xa bank_mask:0xf
	v_max_u32_dpp v26, v26, v26 row_bcast:31 row_mask:0xc bank_mask:0xf
	v_max_u32_dpp v27, v27, v27 row_bcast:31 row_mask:0xc bank_mask:0xf
	v_max_u32_dpp v28, v28, v28 row_bcast:31 row_mask:0xc bank_mask:0xf
	v_max_u32_dpp v29, v29, v29 row_bcast:31 row_mask:0xc bank_mask:0xf
	v_readlane_b32 s14, v26, 63
	v_readlane_b32 s15, v27, 63
	v_readlane_b32 s34, v28, 63
	v_readlane_b32 s35, v29, 63
	v_writelane_b32 v82, s14, 1
	v_writelane_b32 v83, s15, 1
	v_writelane_b32 v84, s34, 1
	v_writelane_b32 v85, s35, 1
	v_cmp_ne_u32_e64 s[42:43], s14, v18
	v_cmp_ne_u32_e64 s[66:67], s14, v22
	v_cmp_ne_u32_e64 s[0:1], s15, v19
	v_cmp_ne_u32_e32 vcc, s15, v23
	v_cndmask_b32_e64 v18, 0, v18, s[42:43]
	v_cndmask_b32_e64 v22, 0, v22, s[66:67]
	v_cndmask_b32_e64 v19, 0, v19, s[0:1]
	v_cndmask_b32_e32 v23, 0, v23, vcc
	v_cmp_ne_u32_e64 s[42:43], s34, v20
	v_cmp_ne_u32_e64 s[66:67], s34, v24
	v_cmp_ne_u32_e64 s[0:1], s35, v21
	v_cmp_ne_u32_e32 vcc, s35, v25
	v_cndmask_b32_e64 v20, 0, v20, s[42:43]
	v_cndmask_b32_e64 v24, 0, v24, s[66:67]
	v_cndmask_b32_e64 v21, 0, v21, s[0:1]
	v_cndmask_b32_e32 v25, 0, v25, vcc
	v_max_u32_e32 v26, v18, v22
	v_max_u32_e32 v27, v19, v23
	v_max_u32_e32 v28, v20, v24
	v_max_u32_e32 v29, v21, v25
	v_max_u32_dpp v26, v26, v26 quad_perm:[1,0,3,2] row_mask:0xf bank_mask:0xf
	v_max_u32_dpp v27, v27, v27 quad_perm:[1,0,3,2] row_mask:0xf bank_mask:0xf
	v_max_u32_dpp v28, v28, v28 quad_perm:[1,0,3,2] row_mask:0xf bank_mask:0xf
	v_max_u32_dpp v29, v29, v29 quad_perm:[1,0,3,2] row_mask:0xf bank_mask:0xf
	v_max_u32_dpp v26, v26, v26 quad_perm:[2,3,0,1] row_mask:0xf bank_mask:0xf
	v_max_u32_dpp v27, v27, v27 quad_perm:[2,3,0,1] row_mask:0xf bank_mask:0xf
	v_max_u32_dpp v28, v28, v28 quad_perm:[2,3,0,1] row_mask:0xf bank_mask:0xf
	v_max_u32_dpp v29, v29, v29 quad_perm:[2,3,0,1] row_mask:0xf bank_mask:0xf
	v_max_u32_dpp v26, v26, v26 row_half_mirror row_mask:0xf bank_mask:0xf
	v_max_u32_dpp v27, v27, v27 row_half_mirror row_mask:0xf bank_mask:0xf
	v_max_u32_dpp v28, v28, v28 row_half_mirror row_mask:0xf bank_mask:0xf
	v_max_u32_dpp v29, v29, v29 row_half_mirror row_mask:0xf bank_mask:0xf
	v_max_u32_dpp v26, v26, v26 row_mirror row_mask:0xf bank_mask:0xf
	v_max_u32_dpp v27, v27, v27 row_mirror row_mask:0xf bank_mask:0xf
	v_max_u32_dpp v28, v28, v28 row_mirror row_mask:0xf bank_mask:0xf
	v_max_u32_dpp v29, v29, v29 row_mirror row_mask:0xf bank_mask:0xf
	v_max_u32_dpp v26, v26, v26 row_bcast:15 row_mask:0xa bank_mask:0xf
	v_max_u32_dpp v27, v27, v27 row_bcast:15 row_mask:0xa bank_mask:0xf
	v_max_u32_dpp v28, v28, v28 row_bcast:15 row_mask:0xa bank_mask:0xf
; __device__ __forceinline__ void nsa_quad_pre(int bg, int quad, const bf16_t* Q, const bf16_t* KV, const bf16_t* KCMP, const bf16_t* VCMPT, const float* GN, bf16_t* ONSA, ...
;     ...
;             for (int it = 0; it < 13; ++it) {
;                 unsigned m = k0 > k1 ? k0 : k1;
; #pragma unroll
;                 for (int off = 32; off >= 1; off >>= 1) { const unsigned o = (unsigned)__shfl_xor((int)m, off); m = o > m ? o : m; }
;                 if (k0 == m) k0 = 0u; if (k1 == m) k1 = 0u;
;                 if (lane == 0) selq[tt * 16 + it] = 127 - (int)(m & 127u);
;             }
	v_max_u32_dpp v29, v29, v29 row_bcast:15 row_mask:0xa bank_mask:0xf
	v_max_u32_dpp v26, v26, v26 row_bcast:31 row_mask:0xc bank_mask:0xf
	v_max_u32_dpp v27, v27, v27 row_bcast:31 row_mask:0xc bank_mask:0xf
	v_max_u32_dpp v28, v28, v28 row_bcast:31 row_mask:0xc bank_mask:0xf
	v_max_u32_dpp v29, v29, v29 row_bcast:31 row_mask:0xc bank_mask:0xf
	v_readlane_b32 s14, v26, 63
	v_readlane_b32 s15, v27, 63
	v_readlane_b32 s34, v28, 63
	v_readlane_b32 s35, v29, 63
	v_writelane_b32 v82, s14, 2
	v_writelane_b32 v83, s15, 2
	v_writelane_b32 v84, s34, 2
	v_writelane_b32 v85, s35, 2
	v_cmp_ne_u32_e64 s[42:43], s14, v18
	v_cmp_ne_u32_e64 s[66:67], s14, v22
	v_cmp_ne_u32_e64 s[0:1], s15, v19
	v_cmp_ne_u32_e32 vcc, s15, v23
	v_cndmask_b32_e64 v18, 0, v18, s[42:43]
	v_cndmask_b32_e64 v22, 0, v22, s[66:67]
	v_cndmask_b32_e64 v19, 0, v19, s[0:1]
	v_cndmask_b32_e32 v23, 0, v23, vcc
	v_cmp_ne_u32_e64 s[42:43], s34, v20
	v_cmp_ne_u32_e64 s[66:67], s34, v24
	v_cmp_ne_u32_e64 s[0:1], s35, v21
	v_cmp_ne_u32_e32 vcc, s35, v25
	v_cndmask_b32_e64 v20, 0, v20, s[42:43]
	v_cndmask_b32_e64 v24, 0, v24, s[66:67]
	v_cndmask_b32_e64 v21, 0, v21, s[0:1]
	v_cndmask_b32_e32 v25, 0, v25, vcc
	v_max_u32_e32 v26, v18, v22
	v_max_u32_e32 v27, v19, v23
	v_max_u32_e32 v28, v20, v24
	v_max_u32_e32 v29, v21, v25
	v_max_u32_dpp v26, v26, v26 quad_perm:[1,0,3,2] row_mask:0xf bank_mask:0xf
	v_max_u32_dpp v27, v27, v27 quad_perm:[1,0,3,2] row_mask:0xf bank_mask:0xf
	v_max_u32_dpp v28, v28, v28 quad_perm:[1,0,3,2] row_mask:0xf bank_mask:0xf
	v_max_u32_dpp v29, v29, v29 quad_perm:[1,0,3,2] row_mask:0xf bank_mask:0xf
	v_max_u32_dpp v26, v26, v26 quad_perm:[2,3,0,1] row_mask:0xf bank_mask:0xf
	v_max_u32_dpp v27, v27, v27 quad_perm:[2,3,0,1] row_mask:0xf bank_mask:0xf
	v_max_u32_dpp v28, v28, v28 quad_perm:[2,3,0,1] row_mask:0xf bank_mask:0xf
	v_max_u32_dpp v29, v29, v29 quad_perm:[2,3,0,1] row_mask:0xf bank_mask:0xf
	v_max_u32_dpp v26, v26, v26 row_half_mirror row_mask:0xf bank_mask:0xf
	v_max_u32_dpp v27, v27, v27 row_half_mirror row_mask:0xf bank_mask:0xf
	v_max_u32_dpp v28, v28, v28 row_half_mirror row_mask:0xf bank_mask:0xf
	v_max_u32_dpp v29, v29, v29 row_half_mirror row_mask:0xf bank_mask:0xf
	v_max_u32_dpp v26, v26, v26 row_mirror row_mask:0xf bank_mask:0xf
	v_max_u32_dpp v27, v27, v27 row_mirror row_mask:0xf bank_mask:0xf
	v_max_u32_dpp v28, v28, v28 row_mirror row_mask:0xf bank_mask:0xf
	v_max_u32_dpp v29, v29, v29 row_mirror row_mask:0xf bank_mask:0xf
	v_max_u32_dpp v26, v26, v26 row_bcast:15 row_mask:0xa bank_mask:0xf
	v_max_u32_dpp v27, v27, v27 row_bcast:15 row_mask:0xa bank_mask:0xf
	v_max_u32_dpp v28, v28, v28 row_bcast:15 row_mask:0xa bank_mask:0xf
	v_max_u32_dpp v29, v29, v29 row_bcast:15 row_mask:0xa bank_mask:0xf
	v_max_u32_dpp v26, v26, v26 row_bcast:31 row_mask:0xc bank_mask:0xf
	v_max_u32_dpp v27, v27, v27 row_bcast:31 row_mask:0xc bank_mask:0xf
	v_max_u32_dpp v28, v28, v28 row_bcast:31 row_mask:0xc bank_mask:0xf
	v_max_u32_dpp v29, v29, v29 row_bcast:31 row_mask:0xc bank_mask:0xf
	v_readlane_b32 s14, v26, 63
	v_readlane_b32 s15, v27, 63
	v_readlane_b32 s34, v28, 63
	v_readlane_b32 s35, v29, 63
	v_writelane_b32 v82, s14, 3
	v_writelane_b32 v83, s15, 3
	v_writelane_b32 v84, s34, 3
	v_writelane_b32 v85, s35, 3
	v_cmp_ne_u32_e64 s[42:43], s14, v18
	v_cmp_ne_u32_e64 s[66:67], s14, v22
	v_cmp_ne_u32_e64 s[0:1], s15, v19
	v_cmp_ne_u32_e32 vcc, s15, v23
	v_cndmask_b32_e64 v18, 0, v18, s[42:43]
	v_cndmask_b32_e64 v22, 0, v22, s[66:67]
	v_cndmask_b32_e64 v19, 0, v19, s[0:1]
	v_cndmask_b32_e32 v23, 0, v23, vcc
	v_cmp_ne_u32_e64 s[42:43], s34, v20
	v_cmp_ne_u32_e64 s[66:67], s34, v24
	v_cmp_ne_u32_e64 s[0:1], s35, v21
	v_cmp_ne_u32_e32 vcc, s35, v25
	v_cndmask_b32_e64 v20, 0, v20, s[42:43]
	v_cndmask_b32_e64 v24, 0, v24, s[66:67]
	v_cndmask_b32_e64 v21, 0, v21, s[0:1]
	v_cndmask_b32_e32 v25, 0, v25, vcc
	v_max_u32_e32 v26, v18, v22
	v_max_u32_e32 v27, v19, v23
	v_max_u32_e32 v28, v20, v24
	v_max_u32_e32 v29, v21, v25
	v_max_u32_dpp v26, v26, v26 quad_perm:[1,0,3,2] row_mask:0xf bank_mask:0xf
	v_max_u32_dpp v27, v27, v27 quad_perm:[1,0,3,2] row_mask:0xf bank_mask:0xf
	v_max_u32_dpp v28, v28, v28 quad_perm:[1,0,3,2] row_mask:0xf bank_mask:0xf
	v_max_u32_dpp v29, v29, v29 quad_perm:[1,0,3,2] row_mask:0xf bank_mask:0xf
	v_max_u32_dpp v26, v26, v26 quad_perm:[2,3,0,1] row_mask:0xf bank_mask:0xf
	v_max_u32_dpp v27, v27, v27 quad_perm:[2,3,0,1] row_mask:0xf bank_mask:0xf
	v_max_u32_dpp v28, v28, v28 quad_perm:[2,3,0,1] row_mask:0xf bank_mask:0xf
	v_max_u32_dpp v29, v29, v29 quad_perm:[2,3,0,1] row_mask:0xf bank_mask:0xf
	v_max_u32_dpp v26, v26, v26 row_half_mirror row_mask:0xf bank_mask:0xf
	v_max_u32_dpp v27, v27, v27 row_half_mirror row_mask:0xf bank_mask:0xf
	v_max_u32_dpp v28, v28, v28 row_half_mirror row_mask:0xf bank_mask:0xf
	v_max_u32_dpp v29, v29, v29 row_half_mirror row_mask:0xf bank_mask:0xf
	v_max_u32_dpp v26, v26, v26 row_mirror row_mask:0xf bank_mask:0xf
	v_max_u32_dpp v27, v27, v27 row_mirror row_mask:0xf bank_mask:0xf
	v_max_u32_dpp v28, v28, v28 row_mirror row_mask:0xf bank_mask:0xf
	v_max_u32_dpp v29, v29, v29 row_mirror row_mask:0xf bank_mask:0xf
	v_max_u32_dpp v26, v26, v26 row_bcast:15 row_mask:0xa bank_mask:0xf
	v_max_u32_dpp v27, v27, v27 row_bcast:15 row_mask:0xa bank_mask:0xf
	v_max_u32_dpp v28, v28, v28 row_bcast:15 row_mask:0xa bank_mask:0xf
	v_max_u32_dpp v29, v29, v29 row_bcast:15 row_mask:0xa bank_mask:0xf
	v_max_u32_dpp v26, v26, v26 row_bcast:31 row_mask:0xc bank_mask:0xf
	v_max_u32_dpp v27, v27, v27 row_bcast:31 row_mask:0xc bank_mask:0xf
	v_max_u32_dpp v28, v28, v28 row_bcast:31 row_mask:0xc bank_mask:0xf
	v_max_u32_dpp v29, v29, v29 row_bcast:31 row_mask:0xc bank_mask:0xf
; __device__ __forceinline__ void nsa_quad_pre(int bg, int quad, const bf16_t* Q, const bf16_t* KV, const bf16_t* KCMP, const bf16_t* VCMPT, const float* GN, bf16_t* ONSA, ...
;     ...
;             for (int it = 0; it < 13; ++it) {
;                 unsigned m = k0 > k1 ? k0 : k1;
; #pragma unroll
;                 for (int off = 32; off >= 1; off >>= 1) { const unsigned o = (unsigned)__shfl_xor((int)m, off); m = o > m ? o : m; }
;                 if (k0 == m) k0 = 0u; if (k1 == m) k1 = 0u;
;                 if (lane == 0) selq[tt * 16 + it] = 127 - (int)(m & 127u);
;             }
	v_readlane_b32 s14, v26, 63
	v_readlane_b32 s15, v27, 63
	v_readlane_b32 s34, v28, 63
	v_readlane_b32 s35, v29, 63
	v_writelane_b32 v82, s14, 4
	v_writelane_b32 v83, s15, 4
	v_writelane_b32 v84, s34, 4
	v_writelane_b32 v85, s35, 4
	v_cmp_ne_u32_e64 s[42:43], s14, v18
	v_cmp_ne_u32_e64 s[66:67], s14, v22
	v_cmp_ne_u32_e64 s[0:1], s15, v19
	v_cmp_ne_u32_e32 vcc, s15, v23
	v_cndmask_b32_e64 v18, 0, v18, s[42:43]
	v_cndmask_b32_e64 v22, 0, v22, s[66:67]
	v_cndmask_b32_e64 v19, 0, v19, s[0:1]
	v_cndmask_b32_e32 v23, 0, v23, vcc
	v_cmp_ne_u32_e64 s[42:43], s34, v20
	v_cmp_ne_u32_e64 s[66:67], s34, v24
	v_cmp_ne_u32_e64 s[0:1], s35, v21
	v_cmp_ne_u32_e32 vcc, s35, v25
	v_cndmask_b32_e64 v20, 0, v20, s[42:43]
	v_cndmask_b32_e64 v24, 0, v24, s[66:67]
	v_cndmask_b32_e64 v21, 0, v21, s[0:1]
	v_cndmask_b32_e32 v25, 0, v25, vcc
	v_max_u32_e32 v26, v18, v22
	v_max_u32_e32 v27, v19, v23
	v_max_u32_e32 v28, v20, v24
	v_max_u32_e32 v29, v21, v25
	v_max_u32_dpp v26, v26, v26 quad_perm:[1,0,3,2] row_mask:0xf bank_mask:0xf
	v_max_u32_dpp v27, v27, v27 quad_perm:[1,0,3,2] row_mask:0xf bank_mask:0xf
	v_max_u32_dpp v28, v28, v28 quad_perm:[1,0,3,2] row_mask:0xf bank_mask:0xf
	v_max_u32_dpp v29, v29, v29 quad_perm:[1,0,3,2] row_mask:0xf bank_mask:0xf
	v_max_u32_dpp v26, v26, v26 quad_perm:[2,3,0,1] row_mask:0xf bank_mask:0xf
	v_max_u32_dpp v27, v27, v27 quad_perm:[2,3,0,1] row_mask:0xf bank_mask:0xf
	v_max_u32_dpp v28, v28, v28 quad_perm:[2,3,0,1] row_mask:0xf bank_mask:0xf
	v_max_u32_dpp v29, v29, v29 quad_perm:[2,3,0,1] row_mask:0xf bank_mask:0xf
	v_max_u32_dpp v26, v26, v26 row_half_mirror row_mask:0xf bank_mask:0xf
	v_max_u32_dpp v27, v27, v27 row_half_mirror row_mask:0xf bank_mask:0xf
	v_max_u32_dpp v28, v28, v28 row_half_mirror row_mask:0xf bank_mask:0xf
	v_max_u32_dpp v29, v29, v29 row_half_mirror row_mask:0xf bank_mask:0xf
	v_max_u32_dpp v26, v26, v26 row_mirror row_mask:0xf bank_mask:0xf
	v_max_u32_dpp v27, v27, v27 row_mirror row_mask:0xf bank_mask:0xf
	v_max_u32_dpp v28, v28, v28 row_mirror row_mask:0xf bank_mask:0xf
	v_max_u32_dpp v29, v29, v29 row_mirror row_mask:0xf bank_mask:0xf
	v_max_u32_dpp v26, v26, v26 row_bcast:15 row_mask:0xa bank_mask:0xf
	v_max_u32_dpp v27, v27, v27 row_bcast:15 row_mask:0xa bank_mask:0xf
	v_max_u32_dpp v28, v28, v28 row_bcast:15 row_mask:0xa bank_mask:0xf
	v_max_u32_dpp v29, v29, v29 row_bcast:15 row_mask:0xa bank_mask:0xf
	v_max_u32_dpp v26, v26, v26 row_bcast:31 row_mask:0xc bank_mask:0xf
	v_max_u32_dpp v27, v27, v27 row_bcast:31 row_mask:0xc bank_mask:0xf
	v_max_u32_dpp v28, v28, v28 row_bcast:31 row_mask:0xc bank_mask:0xf
	v_max_u32_dpp v29, v29, v29 row_bcast:31 row_mask:0xc bank_mask:0xf
	v_readlane_b32 s14, v26, 63
	v_readlane_b32 s15, v27, 63
	v_readlane_b32 s34, v28, 63
	v_readlane_b32 s35, v29, 63
	v_writelane_b32 v82, s14, 5
	v_writelane_b32 v83, s15, 5
	v_writelane_b32 v84, s34, 5
	v_writelane_b32 v85, s35, 5
	v_cmp_ne_u32_e64 s[42:43], s14, v18
	v_cmp_ne_u32_e64 s[66:67], s14, v22
	v_cmp_ne_u32_e64 s[0:1], s15, v19
	v_cmp_ne_u32_e32 vcc, s15, v23
	v_cndmask_b32_e64 v18, 0, v18, s[42:43]
	v_cndmask_b32_e64 v22, 0, v22, s[66:67]
	v_cndmask_b32_e64 v19, 0, v19, s[0:1]
	v_cndmask_b32_e32 v23, 0, v23, vcc
	v_cmp_ne_u32_e64 s[42:43], s34, v20
	v_cmp_ne_u32_e64 s[66:67], s34, v24
	v_cmp_ne_u32_e64 s[0:1], s35, v21
	v_cmp_ne_u32_e32 vcc, s35, v25
	v_cndmask_b32_e64 v20, 0, v20, s[42:43]
	v_cndmask_b32_e64 v24, 0, v24, s[66:67]
	v_cndmask_b32_e64 v21, 0, v21, s[0:1]
	v_cndmask_b32_e32 v25, 0, v25, vcc
	v_max_u32_e32 v26, v18, v22
	v_max_u32_e32 v27, v19, v23
	v_max_u32_e32 v28, v20, v24
	v_max_u32_e32 v29, v21, v25
	v_max_u32_dpp v26, v26, v26 quad_perm:[1,0,3,2] row_mask:0xf bank_mask:0xf
	v_max_u32_dpp v27, v27, v27 quad_perm:[1,0,3,2] row_mask:0xf bank_mask:0xf
	v_max_u32_dpp v28, v28, v28 quad_perm:[1,0,3,2] row_mask:0xf bank_mask:0xf
	v_max_u32_dpp v29, v29, v29 quad_perm:[1,0,3,2] row_mask:0xf bank_mask:0xf
	v_max_u32_dpp v26, v26, v26 quad_perm:[2,3,0,1] row_mask:0xf bank_mask:0xf
	v_max_u32_dpp v27, v27, v27 quad_perm:[2,3,0,1] row_mask:0xf bank_mask:0xf
	v_max_u32_dpp v28, v28, v28 quad_perm:[2,3,0,1] row_mask:0xf bank_mask:0xf
	v_max_u32_dpp v29, v29, v29 quad_perm:[2,3,0,1] row_mask:0xf bank_mask:0xf
	v_max_u32_dpp v26, v26, v26 row_half_mirror row_mask:0xf bank_mask:0xf
	v_max_u32_dpp v27, v27, v27 row_half_mirror row_mask:0xf bank_mask:0xf
	v_max_u32_dpp v28, v28, v28 row_half_mirror row_mask:0xf bank_mask:0xf
	v_max_u32_dpp v29, v29, v29 row_half_mirror row_mask:0xf bank_mask:0xf
	v_max_u32_dpp v26, v26, v26 row_mirror row_mask:0xf bank_mask:0xf
	v_max_u32_dpp v27, v27, v27 row_mirror row_mask:0xf bank_mask:0xf
	v_max_u32_dpp v28, v28, v28 row_mirror row_mask:0xf bank_mask:0xf
	v_max_u32_dpp v29, v29, v29 row_mirror row_mask:0xf bank_mask:0xf
	v_max_u32_dpp v26, v26, v26 row_bcast:15 row_mask:0xa bank_mask:0xf
	v_max_u32_dpp v27, v27, v27 row_bcast:15 row_mask:0xa bank_mask:0xf
	v_max_u32_dpp v28, v28, v28 row_bcast:15 row_mask:0xa bank_mask:0xf
	v_max_u32_dpp v29, v29, v29 row_bcast:15 row_mask:0xa bank_mask:0xf
	v_max_u32_dpp v26, v26, v26 row_bcast:31 row_mask:0xc bank_mask:0xf
	v_max_u32_dpp v27, v27, v27 row_bcast:31 row_mask:0xc bank_mask:0xf
	v_max_u32_dpp v28, v28, v28 row_bcast:31 row_mask:0xc bank_mask:0xf
	v_max_u32_dpp v29, v29, v29 row_bcast:31 row_mask:0xc bank_mask:0xf
	v_readlane_b32 s14, v26, 63
	v_readlane_b32 s15, v27, 63
	v_readlane_b32 s34, v28, 63
	v_readlane_b32 s35, v29, 63
	v_writelane_b32 v82, s14, 6
	v_writelane_b32 v83, s15, 6
	v_writelane_b32 v84, s34, 6
	v_writelane_b32 v85, s35, 6
	v_cmp_ne_u32_e64 s[42:43], s14, v18
	v_cmp_ne_u32_e64 s[66:67], s14, v22
; __device__ __forceinline__ void nsa_quad_pre(int bg, int quad, const bf16_t* Q, const bf16_t* KV, const bf16_t* KCMP, const bf16_t* VCMPT, const float* GN, bf16_t* ONSA, ...
;     ...
;             for (int it = 0; it < 13; ++it) {
;                 unsigned m = k0 > k1 ? k0 : k1;
; #pragma unroll
;                 for (int off = 32; off >= 1; off >>= 1) { const unsigned o = (unsigned)__shfl_xor((int)m, off); m = o > m ? o : m; }
;                 if (k0 == m) k0 = 0u; if (k1 == m) k1 = 0u;
;                 if (lane == 0) selq[tt * 16 + it] = 127 - (int)(m & 127u);
;             }
	v_cmp_ne_u32_e64 s[0:1], s15, v19
	v_cmp_ne_u32_e32 vcc, s15, v23
	v_cndmask_b32_e64 v18, 0, v18, s[42:43]
	v_cndmask_b32_e64 v22, 0, v22, s[66:67]
	v_cndmask_b32_e64 v19, 0, v19, s[0:1]
	v_cndmask_b32_e32 v23, 0, v23, vcc
	v_cmp_ne_u32_e64 s[42:43], s34, v20
	v_cmp_ne_u32_e64 s[66:67], s34, v24
	v_cmp_ne_u32_e64 s[0:1], s35, v21
	v_cmp_ne_u32_e32 vcc, s35, v25
	v_cndmask_b32_e64 v20, 0, v20, s[42:43]
	v_cndmask_b32_e64 v24, 0, v24, s[66:67]
	v_cndmask_b32_e64 v21, 0, v21, s[0:1]
	v_cndmask_b32_e32 v25, 0, v25, vcc
	v_max_u32_e32 v26, v18, v22
	v_max_u32_e32 v27, v19, v23
	v_max_u32_e32 v28, v20, v24
	v_max_u32_e32 v29, v21, v25
	v_max_u32_dpp v26, v26, v26 quad_perm:[1,0,3,2] row_mask:0xf bank_mask:0xf
	v_max_u32_dpp v27, v27, v27 quad_perm:[1,0,3,2] row_mask:0xf bank_mask:0xf
	v_max_u32_dpp v28, v28, v28 quad_perm:[1,0,3,2] row_mask:0xf bank_mask:0xf
	v_max_u32_dpp v29, v29, v29 quad_perm:[1,0,3,2] row_mask:0xf bank_mask:0xf
	v_max_u32_dpp v26, v26, v26 quad_perm:[2,3,0,1] row_mask:0xf bank_mask:0xf
	v_max_u32_dpp v27, v27, v27 quad_perm:[2,3,0,1] row_mask:0xf bank_mask:0xf
	v_max_u32_dpp v28, v28, v28 quad_perm:[2,3,0,1] row_mask:0xf bank_mask:0xf
	v_max_u32_dpp v29, v29, v29 quad_perm:[2,3,0,1] row_mask:0xf bank_mask:0xf
	v_max_u32_dpp v26, v26, v26 row_half_mirror row_mask:0xf bank_mask:0xf
	v_max_u32_dpp v27, v27, v27 row_half_mirror row_mask:0xf bank_mask:0xf
	v_max_u32_dpp v28, v28, v28 row_half_mirror row_mask:0xf bank_mask:0xf
	v_max_u32_dpp v29, v29, v29 row_half_mirror row_mask:0xf bank_mask:0xf
	v_max_u32_dpp v26, v26, v26 row_mirror row_mask:0xf bank_mask:0xf
	v_max_u32_dpp v27, v27, v27 row_mirror row_mask:0xf bank_mask:0xf
	v_max_u32_dpp v28, v28, v28 row_mirror row_mask:0xf bank_mask:0xf
	v_max_u32_dpp v29, v29, v29 row_mirror row_mask:0xf bank_mask:0xf
	v_max_u32_dpp v26, v26, v26 row_bcast:15 row_mask:0xa bank_mask:0xf
	v_max_u32_dpp v27, v27, v27 row_bcast:15 row_mask:0xa bank_mask:0xf
	v_max_u32_dpp v28, v28, v28 row_bcast:15 row_mask:0xa bank_mask:0xf
	v_max_u32_dpp v29, v29, v29 row_bcast:15 row_mask:0xa bank_mask:0xf
	v_max_u32_dpp v26, v26, v26 row_bcast:31 row_mask:0xc bank_mask:0xf
	v_max_u32_dpp v27, v27, v27 row_bcast:31 row_mask:0xc bank_mask:0xf
	v_max_u32_dpp v28, v28, v28 row_bcast:31 row_mask:0xc bank_mask:0xf
	v_max_u32_dpp v29, v29, v29 row_bcast:31 row_mask:0xc bank_mask:0xf
	v_readlane_b32 s14, v26, 63
	v_readlane_b32 s15, v27, 63
	v_readlane_b32 s34, v28, 63
	v_readlane_b32 s35, v29, 63
	v_writelane_b32 v82, s14, 7
	v_writelane_b32 v83, s15, 7
	v_writelane_b32 v84, s34, 7
	v_writelane_b32 v85, s35, 7
	v_cmp_ne_u32_e64 s[42:43], s14, v18
	v_cmp_ne_u32_e64 s[66:67], s14, v22
	v_cmp_ne_u32_e64 s[0:1], s15, v19
	v_cmp_ne_u32_e32 vcc, s15, v23
	v_cndmask_b32_e64 v18, 0, v18, s[42:43]
	v_cndmask_b32_e64 v22, 0, v22, s[66:67]
	v_cndmask_b32_e64 v19, 0, v19, s[0:1]
	v_cndmask_b32_e32 v23, 0, v23, vcc
	v_cmp_ne_u32_e64 s[42:43], s34, v20
	v_cmp_ne_u32_e64 s[66:67], s34, v24
	v_cmp_ne_u32_e64 s[0:1], s35, v21
	v_cmp_ne_u32_e32 vcc, s35, v25
	v_cndmask_b32_e64 v20, 0, v20, s[42:43]
	v_cndmask_b32_e64 v24, 0, v24, s[66:67]
	v_cndmask_b32_e64 v21, 0, v21, s[0:1]
	v_cndmask_b32_e32 v25, 0, v25, vcc
	v_max_u32_e32 v26, v18, v22
	v_max_u32_e32 v27, v19, v23
	v_max_u32_e32 v28, v20, v24
	v_max_u32_e32 v29, v21, v25
	v_max_u32_dpp v26, v26, v26 quad_perm:[1,0,3,2] row_mask:0xf bank_mask:0xf
	v_max_u32_dpp v27, v27, v27 quad_perm:[1,0,3,2] row_mask:0xf bank_mask:0xf
	v_max_u32_dpp v28, v28, v28 quad_perm:[1,0,3,2] row_mask:0xf bank_mask:0xf
	v_max_u32_dpp v29, v29, v29 quad_perm:[1,0,3,2] row_mask:0xf bank_mask:0xf
	v_max_u32_dpp v26, v26, v26 quad_perm:[2,3,0,1] row_mask:0xf bank_mask:0xf
	v_max_u32_dpp v27, v27, v27 quad_perm:[2,3,0,1] row_mask:0xf bank_mask:0xf
	v_max_u32_dpp v28, v28, v28 quad_perm:[2,3,0,1] row_mask:0xf bank_mask:0xf
	v_max_u32_dpp v29, v29, v29 quad_perm:[2,3,0,1] row_mask:0xf bank_mask:0xf
	v_max_u32_dpp v26, v26, v26 row_half_mirror row_mask:0xf bank_mask:0xf
	v_max_u32_dpp v27, v27, v27 row_half_mirror row_mask:0xf bank_mask:0xf
	v_max_u32_dpp v28, v28, v28 row_half_mirror row_mask:0xf bank_mask:0xf
	v_max_u32_dpp v29, v29, v29 row_half_mirror row_mask:0xf bank_mask:0xf
	v_max_u32_dpp v26, v26, v26 row_mirror row_mask:0xf bank_mask:0xf
	v_max_u32_dpp v27, v27, v27 row_mirror row_mask:0xf bank_mask:0xf
	v_max_u32_dpp v28, v28, v28 row_mirror row_mask:0xf bank_mask:0xf
	v_max_u32_dpp v29, v29, v29 row_mirror row_mask:0xf bank_mask:0xf
	v_max_u32_dpp v26, v26, v26 row_bcast:15 row_mask:0xa bank_mask:0xf
	v_max_u32_dpp v27, v27, v27 row_bcast:15 row_mask:0xa bank_mask:0xf
	v_max_u32_dpp v28, v28, v28 row_bcast:15 row_mask:0xa bank_mask:0xf
	v_max_u32_dpp v29, v29, v29 row_bcast:15 row_mask:0xa bank_mask:0xf
	v_max_u32_dpp v26, v26, v26 row_bcast:31 row_mask:0xc bank_mask:0xf
	v_max_u32_dpp v27, v27, v27 row_bcast:31 row_mask:0xc bank_mask:0xf
	v_max_u32_dpp v28, v28, v28 row_bcast:31 row_mask:0xc bank_mask:0xf
	v_max_u32_dpp v29, v29, v29 row_bcast:31 row_mask:0xc bank_mask:0xf
	v_readlane_b32 s14, v26, 63
	v_readlane_b32 s15, v27, 63
	v_readlane_b32 s34, v28, 63
	v_readlane_b32 s35, v29, 63
	v_writelane_b32 v82, s14, 8
	v_writelane_b32 v83, s15, 8
	v_writelane_b32 v84, s34, 8
	v_writelane_b32 v85, s35, 8
	v_cmp_ne_u32_e64 s[42:43], s14, v18
	v_cmp_ne_u32_e64 s[66:67], s14, v22
	v_cmp_ne_u32_e64 s[0:1], s15, v19
	v_cmp_ne_u32_e32 vcc, s15, v23
	v_cndmask_b32_e64 v18, 0, v18, s[42:43]
	v_cndmask_b32_e64 v22, 0, v22, s[66:67]
	v_cndmask_b32_e64 v19, 0, v19, s[0:1]
	v_cndmask_b32_e32 v23, 0, v23, vcc
	v_cmp_ne_u32_e64 s[42:43], s34, v20
	v_cmp_ne_u32_e64 s[66:67], s34, v24
	v_cmp_ne_u32_e64 s[0:1], s35, v21
; __device__ __forceinline__ void nsa_quad_pre(int bg, int quad, const bf16_t* Q, const bf16_t* KV, const bf16_t* KCMP, const bf16_t* VCMPT, const float* GN, bf16_t* ONSA, ...
;     ...
;             for (int it = 0; it < 13; ++it) {
;                 unsigned m = k0 > k1 ? k0 : k1;
; #pragma unroll
;                 for (int off = 32; off >= 1; off >>= 1) { const unsigned o = (unsigned)__shfl_xor((int)m, off); m = o > m ? o : m; }
;                 if (k0 == m) k0 = 0u; if (k1 == m) k1 = 0u;
;                 if (lane == 0) selq[tt * 16 + it] = 127 - (int)(m & 127u);
;             }
	v_cmp_ne_u32_e32 vcc, s35, v25
	v_cndmask_b32_e64 v20, 0, v20, s[42:43]
	v_cndmask_b32_e64 v24, 0, v24, s[66:67]
	v_cndmask_b32_e64 v21, 0, v21, s[0:1]
	v_cndmask_b32_e32 v25, 0, v25, vcc
	v_max_u32_e32 v26, v18, v22
	v_max_u32_e32 v27, v19, v23
	v_max_u32_e32 v28, v20, v24
	v_max_u32_e32 v29, v21, v25
	v_max_u32_dpp v26, v26, v26 quad_perm:[1,0,3,2] row_mask:0xf bank_mask:0xf
	v_max_u32_dpp v27, v27, v27 quad_perm:[1,0,3,2] row_mask:0xf bank_mask:0xf
	v_max_u32_dpp v28, v28, v28 quad_perm:[1,0,3,2] row_mask:0xf bank_mask:0xf
	v_max_u32_dpp v29, v29, v29 quad_perm:[1,0,3,2] row_mask:0xf bank_mask:0xf
	v_max_u32_dpp v26, v26, v26 quad_perm:[2,3,0,1] row_mask:0xf bank_mask:0xf
	v_max_u32_dpp v27, v27, v27 quad_perm:[2,3,0,1] row_mask:0xf bank_mask:0xf
	v_max_u32_dpp v28, v28, v28 quad_perm:[2,3,0,1] row_mask:0xf bank_mask:0xf
	v_max_u32_dpp v29, v29, v29 quad_perm:[2,3,0,1] row_mask:0xf bank_mask:0xf
	v_max_u32_dpp v26, v26, v26 row_half_mirror row_mask:0xf bank_mask:0xf
	v_max_u32_dpp v27, v27, v27 row_half_mirror row_mask:0xf bank_mask:0xf
	v_max_u32_dpp v28, v28, v28 row_half_mirror row_mask:0xf bank_mask:0xf
	v_max_u32_dpp v29, v29, v29 row_half_mirror row_mask:0xf bank_mask:0xf
	v_max_u32_dpp v26, v26, v26 row_mirror row_mask:0xf bank_mask:0xf
	v_max_u32_dpp v27, v27, v27 row_mirror row_mask:0xf bank_mask:0xf
	v_max_u32_dpp v28, v28, v28 row_mirror row_mask:0xf bank_mask:0xf
	v_max_u32_dpp v29, v29, v29 row_mirror row_mask:0xf bank_mask:0xf
	v_max_u32_dpp v26, v26, v26 row_bcast:15 row_mask:0xa bank_mask:0xf
	v_max_u32_dpp v27, v27, v27 row_bcast:15 row_mask:0xa bank_mask:0xf
	v_max_u32_dpp v28, v28, v28 row_bcast:15 row_mask:0xa bank_mask:0xf
	v_max_u32_dpp v29, v29, v29 row_bcast:15 row_mask:0xa bank_mask:0xf
	v_max_u32_dpp v26, v26, v26 row_bcast:31 row_mask:0xc bank_mask:0xf
	v_max_u32_dpp v27, v27, v27 row_bcast:31 row_mask:0xc bank_mask:0xf
	v_max_u32_dpp v28, v28, v28 row_bcast:31 row_mask:0xc bank_mask:0xf
	v_max_u32_dpp v29, v29, v29 row_bcast:31 row_mask:0xc bank_mask:0xf
	v_readlane_b32 s14, v26, 63
	v_readlane_b32 s15, v27, 63
	v_readlane_b32 s34, v28, 63
	v_readlane_b32 s35, v29, 63
	v_writelane_b32 v82, s14, 9
	v_writelane_b32 v83, s15, 9
	v_writelane_b32 v84, s34, 9
	v_writelane_b32 v85, s35, 9
	v_cmp_ne_u32_e64 s[42:43], s14, v18
	v_cmp_ne_u32_e64 s[66:67], s14, v22
	v_cmp_ne_u32_e64 s[0:1], s15, v19
	v_cmp_ne_u32_e32 vcc, s15, v23
	v_cndmask_b32_e64 v18, 0, v18, s[42:43]
	v_cndmask_b32_e64 v22, 0, v22, s[66:67]
	v_cndmask_b32_e64 v19, 0, v19, s[0:1]
	v_cndmask_b32_e32 v23, 0, v23, vcc
	v_cmp_ne_u32_e64 s[42:43], s34, v20
	v_cmp_ne_u32_e64 s[66:67], s34, v24
	v_cmp_ne_u32_e64 s[0:1], s35, v21
	v_cmp_ne_u32_e32 vcc, s35, v25
	v_cndmask_b32_e64 v20, 0, v20, s[42:43]
	v_cndmask_b32_e64 v24, 0, v24, s[66:67]
	v_cndmask_b32_e64 v21, 0, v21, s[0:1]
	v_cndmask_b32_e32 v25, 0, v25, vcc
	v_max_u32_e32 v26, v18, v22
	v_max_u32_e32 v27, v19, v23
	v_max_u32_e32 v28, v20, v24
	v_max_u32_e32 v29, v21, v25
	v_max_u32_dpp v26, v26, v26 quad_perm:[1,0,3,2] row_mask:0xf bank_mask:0xf
	v_max_u32_dpp v27, v27, v27 quad_perm:[1,0,3,2] row_mask:0xf bank_mask:0xf
	v_max_u32_dpp v28, v28, v28 quad_perm:[1,0,3,2] row_mask:0xf bank_mask:0xf
	v_max_u32_dpp v29, v29, v29 quad_perm:[1,0,3,2] row_mask:0xf bank_mask:0xf
	v_max_u32_dpp v26, v26, v26 quad_perm:[2,3,0,1] row_mask:0xf bank_mask:0xf
	v_max_u32_dpp v27, v27, v27 quad_perm:[2,3,0,1] row_mask:0xf bank_mask:0xf
	v_max_u32_dpp v28, v28, v28 quad_perm:[2,3,0,1] row_mask:0xf bank_mask:0xf
	v_max_u32_dpp v29, v29, v29 quad_perm:[2,3,0,1] row_mask:0xf bank_mask:0xf
	v_max_u32_dpp v26, v26, v26 row_half_mirror row_mask:0xf bank_mask:0xf
	v_max_u32_dpp v27, v27, v27 row_half_mirror row_mask:0xf bank_mask:0xf
	v_max_u32_dpp v28, v28, v28 row_half_mirror row_mask:0xf bank_mask:0xf
	v_max_u32_dpp v29, v29, v29 row_half_mirror row_mask:0xf bank_mask:0xf
	v_max_u32_dpp v26, v26, v26 row_mirror row_mask:0xf bank_mask:0xf
	v_max_u32_dpp v27, v27, v27 row_mirror row_mask:0xf bank_mask:0xf
	v_max_u32_dpp v28, v28, v28 row_mirror row_mask:0xf bank_mask:0xf
	v_max_u32_dpp v29, v29, v29 row_mirror row_mask:0xf bank_mask:0xf
	v_max_u32_dpp v26, v26, v26 row_bcast:15 row_mask:0xa bank_mask:0xf
	v_max_u32_dpp v27, v27, v27 row_bcast:15 row_mask:0xa bank_mask:0xf
	v_max_u32_dpp v28, v28, v28 row_bcast:15 row_mask:0xa bank_mask:0xf
	v_max_u32_dpp v29, v29, v29 row_bcast:15 row_mask:0xa bank_mask:0xf
	v_max_u32_dpp v26, v26, v26 row_bcast:31 row_mask:0xc bank_mask:0xf
	v_max_u32_dpp v27, v27, v27 row_bcast:31 row_mask:0xc bank_mask:0xf
	v_max_u32_dpp v28, v28, v28 row_bcast:31 row_mask:0xc bank_mask:0xf
	v_max_u32_dpp v29, v29, v29 row_bcast:31 row_mask:0xc bank_mask:0xf
	v_readlane_b32 s14, v26, 63
	v_readlane_b32 s15, v27, 63
	v_readlane_b32 s34, v28, 63
	v_readlane_b32 s35, v29, 63
	v_writelane_b32 v82, s14, 10
	v_writelane_b32 v83, s15, 10
	v_writelane_b32 v84, s34, 10
	v_writelane_b32 v85, s35, 10
	v_cmp_ne_u32_e64 s[42:43], s14, v18
	v_cmp_ne_u32_e64 s[66:67], s14, v22
	v_cmp_ne_u32_e64 s[0:1], s15, v19
	v_cmp_ne_u32_e32 vcc, s15, v23
	v_cndmask_b32_e64 v18, 0, v18, s[42:43]
	v_cndmask_b32_e64 v22, 0, v22, s[66:67]
	v_cndmask_b32_e64 v19, 0, v19, s[0:1]
	v_cndmask_b32_e32 v23, 0, v23, vcc
	v_cmp_ne_u32_e64 s[42:43], s34, v20
	v_cmp_ne_u32_e64 s[66:67], s34, v24
	v_cmp_ne_u32_e64 s[0:1], s35, v21
	v_cmp_ne_u32_e32 vcc, s35, v25
	v_cndmask_b32_e64 v20, 0, v20, s[42:43]
	v_cndmask_b32_e64 v24, 0, v24, s[66:67]
	v_cndmask_b32_e64 v21, 0, v21, s[0:1]
	v_cndmask_b32_e32 v25, 0, v25, vcc
	v_max_u32_e32 v26, v18, v22
	v_max_u32_e32 v27, v19, v23
	v_max_u32_e32 v28, v20, v24
; __device__ __forceinline__ void nsa_quad_pre(int bg, int quad, const bf16_t* Q, const bf16_t* KV, const bf16_t* KCMP, const bf16_t* VCMPT, const float* GN, bf16_t* ONSA, ...
;     ...
;             for (int it = 0; it < 13; ++it) {
;                 unsigned m = k0 > k1 ? k0 : k1;
; #pragma unroll
;                 for (int off = 32; off >= 1; off >>= 1) { const unsigned o = (unsigned)__shfl_xor((int)m, off); m = o > m ? o : m; }
;                 if (k0 == m) k0 = 0u; if (k1 == m) k1 = 0u;
;                 if (lane == 0) selq[tt * 16 + it] = 127 - (int)(m & 127u);
;             }
;             if (lane == 0) { selq[tt * 16 + 13] = 0; selq[tt * 16 + 14] = cur - 1; selq[tt * 16 + 15] = cur; }
	v_max_u32_e32 v29, v21, v25
	v_max_u32_dpp v26, v26, v26 quad_perm:[1,0,3,2] row_mask:0xf bank_mask:0xf
	v_max_u32_dpp v27, v27, v27 quad_perm:[1,0,3,2] row_mask:0xf bank_mask:0xf
	v_max_u32_dpp v28, v28, v28 quad_perm:[1,0,3,2] row_mask:0xf bank_mask:0xf
	v_max_u32_dpp v29, v29, v29 quad_perm:[1,0,3,2] row_mask:0xf bank_mask:0xf
	v_max_u32_dpp v26, v26, v26 quad_perm:[2,3,0,1] row_mask:0xf bank_mask:0xf
	v_max_u32_dpp v27, v27, v27 quad_perm:[2,3,0,1] row_mask:0xf bank_mask:0xf
	v_max_u32_dpp v28, v28, v28 quad_perm:[2,3,0,1] row_mask:0xf bank_mask:0xf
	v_max_u32_dpp v29, v29, v29 quad_perm:[2,3,0,1] row_mask:0xf bank_mask:0xf
	v_max_u32_dpp v26, v26, v26 row_half_mirror row_mask:0xf bank_mask:0xf
	v_max_u32_dpp v27, v27, v27 row_half_mirror row_mask:0xf bank_mask:0xf
	v_max_u32_dpp v28, v28, v28 row_half_mirror row_mask:0xf bank_mask:0xf
	v_max_u32_dpp v29, v29, v29 row_half_mirror row_mask:0xf bank_mask:0xf
	v_max_u32_dpp v26, v26, v26 row_mirror row_mask:0xf bank_mask:0xf
	v_max_u32_dpp v27, v27, v27 row_mirror row_mask:0xf bank_mask:0xf
	v_max_u32_dpp v28, v28, v28 row_mirror row_mask:0xf bank_mask:0xf
	v_max_u32_dpp v29, v29, v29 row_mirror row_mask:0xf bank_mask:0xf
	v_max_u32_dpp v26, v26, v26 row_bcast:15 row_mask:0xa bank_mask:0xf
	v_max_u32_dpp v27, v27, v27 row_bcast:15 row_mask:0xa bank_mask:0xf
	v_max_u32_dpp v28, v28, v28 row_bcast:15 row_mask:0xa bank_mask:0xf
	v_max_u32_dpp v29, v29, v29 row_bcast:15 row_mask:0xa bank_mask:0xf
	v_max_u32_dpp v26, v26, v26 row_bcast:31 row_mask:0xc bank_mask:0xf
	v_max_u32_dpp v27, v27, v27 row_bcast:31 row_mask:0xc bank_mask:0xf
	v_max_u32_dpp v28, v28, v28 row_bcast:31 row_mask:0xc bank_mask:0xf
	v_max_u32_dpp v29, v29, v29 row_bcast:31 row_mask:0xc bank_mask:0xf
	v_readlane_b32 s14, v26, 63
	v_readlane_b32 s15, v27, 63
	v_readlane_b32 s34, v28, 63
	v_readlane_b32 s35, v29, 63
	v_writelane_b32 v82, s14, 11
	v_writelane_b32 v83, s15, 11
	v_writelane_b32 v84, s34, 11
	v_writelane_b32 v85, s35, 11
	v_cmp_ne_u32_e64 s[42:43], s14, v18
	v_cmp_ne_u32_e64 s[66:67], s14, v22
	v_cmp_ne_u32_e64 s[0:1], s15, v19
	v_cmp_ne_u32_e32 vcc, s15, v23
	v_cndmask_b32_e64 v18, 0, v18, s[42:43]
	v_cndmask_b32_e64 v22, 0, v22, s[66:67]
	v_cndmask_b32_e64 v19, 0, v19, s[0:1]
	v_cndmask_b32_e32 v23, 0, v23, vcc
	v_cmp_ne_u32_e64 s[42:43], s34, v20
	v_cmp_ne_u32_e64 s[66:67], s34, v24
	v_cmp_ne_u32_e64 s[0:1], s35, v21
	v_cmp_ne_u32_e32 vcc, s35, v25
	v_cndmask_b32_e64 v20, 0, v20, s[42:43]
	v_cndmask_b32_e64 v24, 0, v24, s[66:67]
	v_cndmask_b32_e64 v21, 0, v21, s[0:1]
	v_cndmask_b32_e32 v25, 0, v25, vcc
	v_max_u32_e32 v26, v18, v22
	v_max_u32_e32 v27, v19, v23
	v_max_u32_e32 v28, v20, v24
	v_max_u32_e32 v29, v21, v25
	v_max_u32_dpp v26, v26, v26 quad_perm:[1,0,3,2] row_mask:0xf bank_mask:0xf
	v_max_u32_dpp v27, v27, v27 quad_perm:[1,0,3,2] row_mask:0xf bank_mask:0xf
	v_max_u32_dpp v28, v28, v28 quad_perm:[1,0,3,2] row_mask:0xf bank_mask:0xf
	v_max_u32_dpp v29, v29, v29 quad_perm:[1,0,3,2] row_mask:0xf bank_mask:0xf
	v_max_u32_dpp v26, v26, v26 quad_perm:[2,3,0,1] row_mask:0xf bank_mask:0xf
	v_max_u32_dpp v27, v27, v27 quad_perm:[2,3,0,1] row_mask:0xf bank_mask:0xf
	v_max_u32_dpp v28, v28, v28 quad_perm:[2,3,0,1] row_mask:0xf bank_mask:0xf
	v_max_u32_dpp v29, v29, v29 quad_perm:[2,3,0,1] row_mask:0xf bank_mask:0xf
	v_max_u32_dpp v26, v26, v26 row_half_mirror row_mask:0xf bank_mask:0xf
	v_max_u32_dpp v27, v27, v27 row_half_mirror row_mask:0xf bank_mask:0xf
	v_max_u32_dpp v28, v28, v28 row_half_mirror row_mask:0xf bank_mask:0xf
	v_max_u32_dpp v29, v29, v29 row_half_mirror row_mask:0xf bank_mask:0xf
	v_max_u32_dpp v26, v26, v26 row_mirror row_mask:0xf bank_mask:0xf
	v_max_u32_dpp v27, v27, v27 row_mirror row_mask:0xf bank_mask:0xf
	v_max_u32_dpp v28, v28, v28 row_mirror row_mask:0xf bank_mask:0xf
	v_max_u32_dpp v29, v29, v29 row_mirror row_mask:0xf bank_mask:0xf
	v_max_u32_dpp v26, v26, v26 row_bcast:15 row_mask:0xa bank_mask:0xf
	v_max_u32_dpp v27, v27, v27 row_bcast:15 row_mask:0xa bank_mask:0xf
	v_max_u32_dpp v28, v28, v28 row_bcast:15 row_mask:0xa bank_mask:0xf
	v_max_u32_dpp v29, v29, v29 row_bcast:15 row_mask:0xa bank_mask:0xf
	v_max_u32_dpp v26, v26, v26 row_bcast:31 row_mask:0xc bank_mask:0xf
	v_max_u32_dpp v27, v27, v27 row_bcast:31 row_mask:0xc bank_mask:0xf
	v_max_u32_dpp v28, v28, v28 row_bcast:31 row_mask:0xc bank_mask:0xf
	v_max_u32_dpp v29, v29, v29 row_bcast:31 row_mask:0xc bank_mask:0xf
	v_readlane_b32 s14, v26, 63
	v_readlane_b32 s15, v27, 63
	v_readlane_b32 s34, v28, 63
	v_readlane_b32 s35, v29, 63
	v_writelane_b32 v82, s14, 12
	v_writelane_b32 v83, s15, 12
	v_writelane_b32 v84, s34, 12
	v_writelane_b32 v85, s35, 12
	v_and_b32_e32 v82, 127, v82
	v_sub_u32_e32 v82, 127, v82
	v_and_b32_e32 v83, 127, v83
	v_sub_u32_e32 v83, 127, v83
	v_and_b32_e32 v84, 127, v84
	v_sub_u32_e32 v84, 127, v84
	v_and_b32_e32 v85, 127, v85
	v_sub_u32_e32 v85, 127, v85
	s_add_i32 s19, s18, -1
	v_mov_b32_e32 v236, s19
	v_mov_b32_e32 v237, s18
	v_cmp_eq_u32_e64 s[14:15], 14, v184
	v_cmp_eq_u32_e64 s[34:35], 15, v184
	s_nop 0
	v_cndmask_b32_e64 v82, v82, v236, s[14:15]
	v_cndmask_b32_e64 v82, v82, v237, s[34:35]
	v_cndmask_b32_e64 v83, v83, v236, s[14:15]
	v_cndmask_b32_e64 v83, v83, v237, s[34:35]
	v_cndmask_b32_e64 v84, v84, v236, s[14:15]
	v_cndmask_b32_e64 v84, v84, v237, s[34:35]
	v_cndmask_b32_e64 v85, v85, v236, s[14:15]
	v_cndmask_b32_e64 v85, v85, v237, s[34:35]
	s_and_saveexec_b64 s[42:43], s[6:7]
	ds_write_b32 v196, v82 offset:51264
	ds_write_b32 v196, v83 offset:51328
	ds_write_b32 v196, v84 offset:51392
	ds_write_b32 v196, v85 offset:51456
	s_or_b64 exec, exec, s[42:43]
	s_branch .Ltopk_done_q0

; __device__ __forceinline__ void nsa_quad_pre(int bg, int quad, const bf16_t* Q, const bf16_t* KV, const bf16_t* KCMP, const bf16_t* VCMPT, const float* GN, bf16_t* ONSA, ...
;     ...
;     const int w_lo = (t0 - 511 > 0 ? t0 - 511 : 0) >> 6, w_hi = t0 >> 6;
;     f32x4 oc[4] = {z4, z4, z4, z4};
;     const int tl = t0 + 3, nvmax = tl >= 31 ? ((tl - 31) >> 4) + 1 : 0, ngr = (nvmax + 63) >> 6;
;     if (ngr > 0) {
;         float ls[4] = {0.f, 0.f, 0.f, 0.f};
;         load_k(KF, KP_C(0));
;         for (int gr = 0; gr < ngr; ++gr) {
;             qk_scores(KF, qf, sc);
;             load_k(KF, KP_C(gr + 1 < ngr ? gr + 1 : 0));
;             cmp_sm1(sc, gr, t0, bt, ls, r16);
;         }
.Ltopk_done_q0:
	s_nop 0
	s_waitcnt lgkmcnt(0)
	s_lshl_b32 s47, s18, 6
	s_add_i32 s47, s47, s80
	s_add_i32 s47, s47, 4
	v_and_b32_e32 v232, 15, v184
	v_and_b32_e32 v234, 3, v232
	v_lshrrev_b32_e32 v235, 2, v232
	s_add_i32 s0, s47, s97
	v_add_u32_e32 v253, s0, v234
	s_and_b32 s1, s88, 3
	s_lshl_b32 s1, s1, 2
	v_add_u32_e32 v0, s1, v235
	v_mul_u32_u24_e32 v99, 0xc0, v253
	v_mul_u32_u24_e32 v0, 12, v0
	v_add_u32_e32 v99, v99, v0
	s_add_u32 s72, s30, 0x38310000
	s_addc_u32 s73, s31, 0
	global_load_dword v227, v99, s[72:73]
	v_mov_b32_e32 v2, 0
	v_mov_b32_e32 v3, 0
	v_mov_b32_e32 v4, 0
	v_mov_b32_e32 v5, 0
	v_mov_b32_e32 v6, 0
	v_mov_b32_e32 v7, 0
	v_mov_b32_e32 v8, 0
	v_mov_b32_e32 v9, 0
	v_mov_b32_e32 v10, 0
	v_mov_b32_e32 v11, 0
	v_mov_b32_e32 v12, 0
	v_mov_b32_e32 v13, 0
	v_mov_b32_e32 v14, 0
	v_mov_b32_e32 v15, 0
	v_mov_b32_e32 v16, 0
	v_mov_b32_e32 v17, 0
	s_sub_i32 s0, s47, 28
	s_ashr_i32 s0, s0, 4
	s_add_i32 s0, s0, 64
	s_ashr_i32 s53, s0, 6
	s_cmp_gt_i32 s47, 27
	s_cselect_b32 s53, s53, 0
	s_sub_i32 s0, s47, 2063
	s_ashr_i32 s52, s0, 10
	s_add_i32 s52, s52, 1
	s_max_i32 s52, s52, 0
	s_min_i32 s52, s52, s53
	v_add_u32_e32 v99, s47, v172
	v_and_b32_e32 v98, 15, v184
	v_mov_b32_e32 v170, 0
	v_mov_b32_e32 v228, v225
	v_mov_b32_e32 v229, v225
	v_mov_b32_e32 v230, v225
	v_mov_b32_e32 v231, v225
	s_mov_b32 s57, 0
.Lcmp_top_q1p1:
	s_cmp_ge_i32 s57, s53
	s_cbranch_scc1 .Lcmp_skip_q1p1
	s_lshl_b32 s0, s75, 13
	s_add_i32 s0, s0, 16448
	v_add_u32_e32 v179, s0, v176
	v_add_u32_e32 v226, v179, v178
	ds_read_b128 v[50:53], v179 offset:0
	ds_read_b128 v[54:57], v226 offset:0
	ds_read_b128 v[58:61], v179 offset:512
	ds_read_b128 v[62:65], v226 offset:512
	ds_read_b128 v[66:69], v179 offset:4096
	ds_read_b128 v[70:73], v226 offset:4096
	ds_read_b128 v[74:77], v179 offset:4608
	ds_read_b128 v[78:81], v226 offset:4608
	s_lshl_b32 s0, s92, 13
	s_add_i32 s0, s0, s33
	s_add_i32 m0, s0, 16448
	s_lshl_b32 s1, s93, 13
	s_add_u32 s72, s68, s1
	s_addc_u32 s73, s69, 0
	global_load_lds_dwordx4 v174, s[72:73]
	s_cmp_eq_u32 s92, 1
	s_cselect_b32 s0, s95, s94
	s_cmp_eq_u32 s92, 2
	s_cselect_b32 m0, s46, s0
	s_lshl_b32 s1, s93, 7
	s_add_u32 s72, s70, s1
	s_addc_u32 s73, s71, 0
	global_load_lds_dwordx4 v175, s[72:73]
	s_add_i32 s93, s93, 1
	s_cmp_ge_i32 s93, s74
	s_cselect_b32 s93, 0, s93
	s_add_i32 s92, s92, 1
	s_cmp_eq_u32 s92, 3
	s_cselect_b32 s92, 0, s92
	s_cmp_lt_i32 s57, s52
	s_cbranch_scc0 .Lcmp_gen_q1p1
	s_waitcnt lgkmcnt(7)
	v_mfma_f32_16x16x32_bf16 v[18:21], v[50:53], v[42:45], v[228:231]
	s_waitcnt lgkmcnt(6)
	v_mfma_f32_16x16x32_bf16 v[18:21], v[54:57], v[46:49], v[18:21]
	s_waitcnt lgkmcnt(5)
	v_mfma_f32_16x16x32_bf16 v[22:25], v[58:61], v[42:45], v[228:231]
	s_waitcnt lgkmcnt(4)
	v_mfma_f32_16x16x32_bf16 v[22:25], v[62:65], v[46:49], v[22:25]
	s_waitcnt lgkmcnt(3)
	v_mfma_f32_16x16x32_bf16 v[26:29], v[66:69], v[42:45], v[228:231]
	s_waitcnt lgkmcnt(2)
	v_mfma_f32_16x16x32_bf16 v[26:29], v[70:73], v[46:49], v[26:29]
	s_waitcnt lgkmcnt(1)
	v_mfma_f32_16x16x32_bf16 v[30:33], v[74:77], v[42:45], v[228:231]
	s_waitcnt lgkmcnt(0)
	v_mfma_f32_16x16x32_bf16 v[30:33], v[78:81], v[46:49], v[30:33]
	v_exp_f32_e32 v18, v18
	v_exp_f32_e32 v19, v19
	v_exp_f32_e32 v20, v20
	v_exp_f32_e32 v21, v21
	v_exp_f32_e32 v22, v22
	v_exp_f32_e32 v23, v23
	v_exp_f32_e32 v24, v24
	v_exp_f32_e32 v25, v25
	v_exp_f32_e32 v26, v26
	v_exp_f32_e32 v27, v27
	v_exp_f32_e32 v28, v28
	v_exp_f32_e32 v29, v29
	v_exp_f32_e32 v30, v30
	v_exp_f32_e32 v31, v31
	v_exp_f32_e32 v32, v32
	v_exp_f32_e32 v33, v33
	v_add_f32_e32 v18, v18, v19
	v_add_f32_e32 v20, v20, v21
	v_add_f32_e32 v22, v22, v23
	v_add_f32_e32 v24, v24, v25
	v_add_f32_e32 v26, v26, v27
	v_add_f32_e32 v28, v28, v29
	v_add_f32_e32 v30, v30, v31
	v_add_f32_e32 v32, v32, v33
	v_add_f32_e32 v18, v18, v20
	v_add_f32_e32 v22, v22, v24
	v_add_f32_e32 v26, v26, v28
	v_add_f32_e32 v30, v30, v32
	v_add_f32_e32 v18, v18, v22
	v_add_f32_e32 v26, v26, v30
	v_add_f32_e32 v18, v18, v26
	v_add_f32_e32 v170, v170, v18
	s_branch .Lcmp_tail_q1p1

; #define LAS __attribute__((address_space(3)))
; __device__ __forceinline__ bf16_t tobf(float x) { return (bf16_t)pk2(x, 0.f); }
; __device__ __forceinline__ float ex2(float x) { return __builtin_amdgcn_exp2f(x); }
; __device__ __forceinline__ void cmp_sm2(const f32x4 (&sc)[4], int gr, int t0, const LAS float* bt, const float (&inv)[4], LAS bf16_t* Pb, LAS float* psum, int r16, int q4) {
; #pragma unroll
;     for (int cc = 0; cc < 4; ++cc) {
;         const int kk = gr * 64 + cc * 16 + r16, cend = kk * 16 + 31;
; #pragma unroll
;         for (int i = 0; i < 4; ++i) { const int dist = t0 + i - cend; float p = dist >= 0 ? ex2(sc[cc][i] + bt[clampd(dist)]) * inv[i] : 0.f;
;             Pb[(4 * q4 + i) * 72 + cc * 16 + r16] = tobf(p); p += __shfl_xor(p, 16); p += __shfl_xor(p, 32); if (q4 == 0) psum[i * 512 + kk] = p; }
;     }
; }
; __device__ __forceinline__ void nsa_quad_pre(int bg, int quad, const bf16_t* Q, const bf16_t* KV, const bf16_t* KCMP, const bf16_t* VCMPT, const float* GN, bf16_t* ONSA, ...
;     ...
;         for (int gr = 0; gr < ngr; ++gr) {
;             const bool more = gr + 1 < ngr;
;             qk_scores(KF, qf, sc);
;             if (more) load_k(KF, KP_C(gr + 1));
;             cmp_sm2(sc, gr, t0, bt, inv, Pb, psum, r16, q4);
;             pv_step(VF, oc, Pb, r16, q4);
;             if (more) load_v(VF, VP_C(gr + 1));
;         }
.Lcmp_top_q1p2:
	s_cmp_ge_i32 s57, s53
	s_cbranch_scc1 .Lcmp_skip_q1p2
	s_lshl_b32 s0, s75, 13
	s_add_i32 s0, s0, 16448
	v_add_u32_e32 v179, s0, v176
	v_add_u32_e32 v226, v179, v178
	ds_read_b128 v[50:53], v179 offset:0
	ds_read_b128 v[54:57], v226 offset:0
	ds_read_b128 v[58:61], v179 offset:512
	ds_read_b128 v[62:65], v226 offset:512
	ds_read_b128 v[66:69], v179 offset:4096
	ds_read_b128 v[70:73], v226 offset:4096
	ds_read_b128 v[74:77], v179 offset:4608
	ds_read_b128 v[78:81], v226 offset:4608
	s_lshl_b32 s0, s92, 13
	s_add_i32 s0, s0, s33
	s_add_i32 m0, s0, 16448
	s_lshl_b32 s1, s93, 13
	s_add_u32 s72, s68, s1
	s_addc_u32 s73, s69, 0
	global_load_lds_dwordx4 v174, s[72:73]
	s_cmp_eq_u32 s92, 1
	s_cselect_b32 s0, s95, s94
	s_cmp_eq_u32 s92, 2
	s_cselect_b32 m0, s46, s0
	s_lshl_b32 s1, s93, 7
	s_add_u32 s72, s70, s1
	s_addc_u32 s73, s71, 0
	global_load_lds_dwordx4 v175, s[72:73]
	s_add_i32 s93, s93, 1
	s_cmp_ge_i32 s93, s74
	s_cselect_b32 s93, 0, s93
	s_add_i32 s92, s92, 1
	s_cmp_eq_u32 s92, 3
	s_cselect_b32 s92, 0, s92
	s_cmp_lt_i32 s57, s52
	s_cbranch_scc0 .Lcmp_gen_q1p2
	s_waitcnt lgkmcnt(7)
	v_mfma_f32_16x16x32_bf16 v[18:21], v[50:53], v[42:45], v[228:231]
	s_waitcnt lgkmcnt(6)
	v_mfma_f32_16x16x32_bf16 v[18:21], v[54:57], v[46:49], v[18:21]
	s_waitcnt lgkmcnt(5)
	v_mfma_f32_16x16x32_bf16 v[22:25], v[58:61], v[42:45], v[228:231]
	s_waitcnt lgkmcnt(4)
	v_mfma_f32_16x16x32_bf16 v[22:25], v[62:65], v[46:49], v[22:25]
	s_waitcnt lgkmcnt(3)
	v_mfma_f32_16x16x32_bf16 v[26:29], v[66:69], v[42:45], v[228:231]
	s_waitcnt lgkmcnt(2)
	v_mfma_f32_16x16x32_bf16 v[26:29], v[70:73], v[46:49], v[26:29]
	s_waitcnt lgkmcnt(1)
	v_mfma_f32_16x16x32_bf16 v[30:33], v[74:77], v[42:45], v[228:231]
	s_waitcnt lgkmcnt(0)
	v_mfma_f32_16x16x32_bf16 v[30:33], v[78:81], v[46:49], v[30:33]
	s_cmp_eq_u32 s75, 1
	s_cselect_b32 s0, s95, s94
	s_cmp_eq_u32 s75, 2
	s_cselect_b32 s0, s46, s0
	v_add_u32_e32 v179, s0, v177
	v_add_u32_e32 v226, v179, v178
	ds_read_b128 v[82:85], v179 offset:0
	ds_read_b128 v[86:89], v226 offset:0
	ds_read_b128 v[90:93], v179 offset:2048
	ds_read_b128 v[94:97], v226 offset:2048
	ds_read_b128 v[236:239], v179 offset:4096
	ds_read_b128 v[240:243], v226 offset:4096
	ds_read_b128 v[244:247], v179 offset:6144
	ds_read_b128 v[248:251], v226 offset:6144
	v_exp_f32_e32 v18, v18
	v_exp_f32_e32 v19, v19
	v_exp_f32_e32 v20, v20
	v_exp_f32_e32 v21, v21
	v_exp_f32_e32 v22, v22
	v_exp_f32_e32 v23, v23
	v_exp_f32_e32 v24, v24
	v_exp_f32_e32 v25, v25
	v_exp_f32_e32 v26, v26
	v_exp_f32_e32 v27, v27
	v_exp_f32_e32 v28, v28
	v_exp_f32_e32 v29, v29
	v_exp_f32_e32 v30, v30
	v_exp_f32_e32 v31, v31
	v_exp_f32_e32 v32, v32
	v_exp_f32_e32 v33, v33
	v_mul_f32_e32 v18, v18, v171
	v_mul_f32_e32 v19, v19, v171
	v_mul_f32_e32 v20, v20, v171
	v_mul_f32_e32 v21, v21, v171
	v_mul_f32_e32 v22, v22, v171
	v_mul_f32_e32 v23, v23, v171
	v_mul_f32_e32 v24, v24, v171
	v_mul_f32_e32 v25, v25, v171
	v_mul_f32_e32 v26, v26, v171
	v_mul_f32_e32 v27, v27, v171
	v_mul_f32_e32 v28, v28, v171
	v_mul_f32_e32 v29, v29, v171
	v_mul_f32_e32 v30, v30, v171
	v_mul_f32_e32 v31, v31, v171
	v_mul_f32_e32 v32, v32, v171
	v_mul_f32_e32 v33, v33, v171
	v_add_f32_dpp v50, v18, v18 row_shr:4 row_mask:0xf bank_mask:0xf
	v_add_f32_dpp v51, v19, v19 row_shr:4 row_mask:0xf bank_mask:0xf
	v_add_f32_dpp v52, v20, v20 row_shr:4 row_mask:0xf bank_mask:0xf
	v_add_f32_dpp v53, v21, v21 row_shr:4 row_mask:0xf bank_mask:0xf
	v_add_f32_dpp v54, v22, v22 row_shr:4 row_mask:0xf bank_mask:0xf
	v_add_f32_dpp v55, v23, v23 row_shr:4 row_mask:0xf bank_mask:0xf
	v_add_f32_dpp v56, v24, v24 row_shr:4 row_mask:0xf bank_mask:0xf
	v_add_f32_dpp v57, v25, v25 row_shr:4 row_mask:0xf bank_mask:0xf
	v_add_f32_dpp v58, v26, v26 row_shr:4 row_mask:0xf bank_mask:0xf
	v_add_f32_dpp v59, v27, v27 row_shr:4 row_mask:0xf bank_mask:0xf
	v_add_f32_dpp v60, v28, v28 row_shr:4 row_mask:0xf bank_mask:0xf
	v_add_f32_dpp v61, v29, v29 row_shr:4 row_mask:0xf bank_mask:0xf
	v_add_f32_dpp v62, v30, v30 row_shr:4 row_mask:0xf bank_mask:0xf
	v_add_f32_dpp v63, v31, v31 row_shr:4 row_mask:0xf bank_mask:0xf
	v_add_f32_dpp v64, v32, v32 row_shr:4 row_mask:0xf bank_mask:0xf
	v_add_f32_dpp v65, v33, v33 row_shr:4 row_mask:0xf bank_mask:0xf
	v_add_f32_dpp v50, v50, v50 row_shr:8 row_mask:0xf bank_mask:0xf
	v_add_f32_dpp v51, v51, v51 row_shr:8 row_mask:0xf bank_mask:0xf
	v_add_f32_dpp v52, v52, v52 row_shr:8 row_mask:0xf bank_mask:0xf
	v_add_f32_dpp v53, v53, v53 row_shr:8 row_mask:0xf bank_mask:0xf
	v_add_f32_dpp v54, v54, v54 row_shr:8 row_mask:0xf bank_mask:0xf
	v_add_f32_dpp v55, v55, v55 row_shr:8 row_mask:0xf bank_mask:0xf
	v_add_f32_dpp v56, v56, v56 row_shr:8 row_mask:0xf bank_mask:0xf
	v_add_f32_dpp v57, v57, v57 row_shr:8 row_mask:0xf bank_mask:0xf
	v_add_f32_dpp v58, v58, v58 row_shr:8 row_mask:0xf bank_mask:0xf
	v_add_f32_dpp v59, v59, v59 row_shr:8 row_mask:0xf bank_mask:0xf
	v_add_f32_dpp v60, v60, v60 row_shr:8 row_mask:0xf bank_mask:0xf
	v_add_f32_dpp v61, v61, v61 row_shr:8 row_mask:0xf bank_mask:0xf
	v_add_f32_dpp v62, v62, v62 row_shr:8 row_mask:0xf bank_mask:0xf
	v_add_f32_dpp v63, v63, v63 row_shr:8 row_mask:0xf bank_mask:0xf
	v_add_f32_dpp v64, v64, v64 row_shr:8 row_mask:0xf bank_mask:0xf
	v_add_f32_dpp v65, v65, v65 row_shr:8 row_mask:0xf bank_mask:0xf
	s_lshl_b32 s0, s57, 8
	v_add_u32_e32 v232, s0, v215
	v_cmp_lt_u32_e32 vcc, 11, v98
	s_nop 0
	s_and_saveexec_b64 s[20:21], vcc
	ds_write_b128 v232, v[50:53] offset:0
	ds_write_b128 v232, v[54:57] offset:16
	ds_write_b128 v232, v[58:61] offset:128
	ds_write_b128 v232, v[62:65] offset:144
	s_or_b64 exec, exec, s[20:21]
	v_cvt_pk_bf16_f32 v216, v18, v19
	v_cvt_pk_bf16_f32 v217, v20, v21
	v_cvt_pk_bf16_f32 v218, v22, v23
	v_cvt_pk_bf16_f32 v219, v24, v25
	v_cvt_pk_bf16_f32 v220, v26, v27
	v_cvt_pk_bf16_f32 v221, v28, v29
	v_cvt_pk_bf16_f32 v222, v30, v31
	v_cvt_pk_bf16_f32 v223, v32, v33
	s_waitcnt lgkmcnt(11)
	v_mfma_f32_16x16x32_bf16 v[2:5], v[82:85], v[216:219], v[2:5]
	s_waitcnt lgkmcnt(10)
	v_mfma_f32_16x16x32_bf16 v[2:5], v[86:89], v[220:223], v[2:5]
	s_waitcnt lgkmcnt(9)
	v_mfma_f32_16x16x32_bf16 v[6:9], v[90:93], v[216:219], v[6:9]
	s_waitcnt lgkmcnt(8)
	v_mfma_f32_16x16x32_bf16 v[6:9], v[94:97], v[220:223], v[6:9]
	s_waitcnt lgkmcnt(7)
	v_mfma_f32_16x16x32_bf16 v[10:13], v[236:239], v[216:219], v[10:13]
	s_waitcnt lgkmcnt(6)
	v_mfma_f32_16x16x32_bf16 v[10:13], v[240:243], v[220:223], v[10:13]
	s_waitcnt lgkmcnt(5)
	v_mfma_f32_16x16x32_bf16 v[14:17], v[244:247], v[216:219], v[14:17]
	s_waitcnt lgkmcnt(4)
	v_mfma_f32_16x16x32_bf16 v[14:17], v[248:251], v[220:223], v[14:17]
	s_branch .Lcmp_tail_q1p2

; #define LAS __attribute__((address_space(3)))
; #define CBAR() asm volatile("" ::: "memory")
; __device__ __forceinline__ bf16_t tobf(float x) { return (bf16_t)pk2(x, 0.f); }
; __device__ __forceinline__ void nsa_quad_pre(int bg, int quad, const bf16_t* Q, const bf16_t* KV, const bf16_t* KCMP, const bf16_t* VCMPT, const float* GN, bf16_t* ONSA, ...
;     ...
;             unsigned k0 = 0u, k1 = 0u;
;             { const int j = lane; if (j >= 1 && j <= cur - 2) { const LAS float* ps = psum + tt * 512 + 4 * j - 1; const float v = ps[0] + ps[1] + ps[2] + ps[3] + ps[4]; k0 = (__builtin_bit_cast(unsigned, v) & ~127u) | (unsigned)(127 - j); } }
;             { const int j = lane + 64; if (j <= cur - 2) { const LAS float* ps = psum + tt * 512 + 4 * j - 1; const float v = ps[0] + ps[1] + ps[2] + ps[3] + ps[4]; k1 = (__builtin_bit_cast(unsigned, v) & ~127u) | (unsigned)(127 - j); } }
;             for (int it = 0; it < 13; ++it) {
;                 unsigned m = k0 > k1 ? k0 : k1;
; #pragma unroll
;                 for (int off = 32; off >= 1; off >>= 1) { const unsigned o = (unsigned)__shfl_xor((int)m, off); m = o > m ? o : m; }
;                 if (k0 == m) k0 = 0u; if (k1 == m) k1 = 0u;
;                 if (lane == 0) selq[tt * 16 + it] = 127 - (int)(m & 127u);
;             }
;             if (lane == 0) { selq[tt * 16 + 13] = 0; selq[tt * 16 + 14] = cur - 1; selq[tt * 16 + 15] = cur; }
;         }
;     }
;     CBAR();
; #pragma unroll
;     for (int tt = 0; tt < 4; ++tt) { const float gc = GN[(size_t)(b * SEQ + t0 + tt) * 48 + (g * 4 + q4) * 3];
;         bf16_t* op = ONSA + (size_t)(b * SEQ + t0 + tt) * 1024 + (g * 4 + q4) * 64 + r16;
; #pragma unroll
;         for (int nt = 0; nt < 4; ++nt) op[nt * 16] = tobf(gc * oc[nt][tt]); }
.Lcmp_tail_q1p2:
	s_add_i32 s75, s75, 1
	s_cmp_eq_u32 s75, 3
	s_cselect_b32 s75, 0, s75
	s_add_i32 s57, s57, 1
	s_cmp_lt_i32 s57, s74
	s_waitcnt vmcnt(2) lgkmcnt(0)
	s_barrier
	s_cbranch_scc1 .Lcmp_top_q1p2
	s_waitcnt lgkmcnt(0)
	v_and_b32_e32 v232, 15, v184
	v_lshrrev_b32_e32 v233, 4, v184
	v_and_b32_e32 v234, 3, v232
	v_lshrrev_b32_e32 v235, 2, v232
	s_add_i32 s0, s47, s97
	v_add_u32_e32 v253, s0, v234
	s_and_b32 s1, s88, 3
	s_lshl_b32 s1, s1, 2
	v_add_u32_e32 v0, s1, v235
	v_lshlrev_b32_e32 v98, 7, v0
	v_lshl_add_u32 v98, v253, 11, v98
	v_lshl_add_u32 v98, v233, 3, v98
	s_add_u32 s14, s30, 0xf900000
	s_addc_u32 s15, s31, 0
	s_waitcnt vmcnt(0)
	v_mul_f32_e32 v2, v2, v227
	v_mul_f32_e32 v3, v3, v227
	v_mul_f32_e32 v4, v4, v227
	v_mul_f32_e32 v5, v5, v227
	v_mul_f32_e32 v6, v6, v227
	v_mul_f32_e32 v7, v7, v227
	v_mul_f32_e32 v8, v8, v227
	v_mul_f32_e32 v9, v9, v227
	v_mul_f32_e32 v10, v10, v227
	v_mul_f32_e32 v11, v11, v227
	v_mul_f32_e32 v12, v12, v227
	v_mul_f32_e32 v13, v13, v227
	v_mul_f32_e32 v14, v14, v227
	v_mul_f32_e32 v15, v15, v227
	v_mul_f32_e32 v16, v16, v227
	v_mul_f32_e32 v17, v17, v227
	v_cvt_pk_bf16_f32 v216, v2, v3
	v_cvt_pk_bf16_f32 v217, v4, v5
	v_cvt_pk_bf16_f32 v218, v6, v7
	v_cvt_pk_bf16_f32 v219, v8, v9
	v_cvt_pk_bf16_f32 v220, v10, v11
	v_cvt_pk_bf16_f32 v221, v12, v13
	v_cvt_pk_bf16_f32 v222, v14, v15
	v_cvt_pk_bf16_f32 v223, v16, v17
	global_store_dwordx2 v98, v[216:217], s[14:15] offset:0
	global_store_dwordx2 v98, v[218:219], s[14:15] offset:32
	global_store_dwordx2 v98, v[220:221], s[14:15] offset:64
	global_store_dwordx2 v98, v[222:223], s[14:15] offset:96
	s_waitcnt lgkmcnt(0)
	s_cmp_gt_i32 s18, 15
	s_cbranch_scc0 .Ltopk_small_q1
	s_lshl_b32 s19, s80, 10
	s_add_i32 s19, s19, 56384
	v_lshlrev_b32_e32 v96, 4, v184
	v_add_u32_e32 v96, s19, v96
	v_add_u32_e32 v97, 0xfffffffc, v96
	v_sub_u32_e32 v94, 127, v184
	v_sub_u32_e32 v95, 63, v184
	s_mov_b32 s54, 0xffffff80
	s_add_i32 s21, s18, -2
	v_add_u32_e32 v236, 64, v184
	ds_read_b32 v86, v97 offset:0
	ds_read_b128 v[50:53], v96 offset:0
	ds_read_b32 v87, v97 offset:1024
	ds_read_b128 v[54:57], v96 offset:1024
	ds_read_b32 v88, v97 offset:2048
	ds_read_b128 v[58:61], v96 offset:2048
	ds_read_b32 v89, v97 offset:3072
	ds_read_b128 v[62:65], v96 offset:3072
	s_waitcnt lgkmcnt(6)
	v_add_f32_e32 v86, v86, v50
	v_add_f32_e32 v86, v86, v51
	v_add_f32_e32 v86, v86, v52
	v_add_f32_e32 v86, v86, v53
	v_and_or_b32 v18, v86, s54, v94
	s_waitcnt lgkmcnt(4)
	v_add_f32_e32 v87, v87, v54
	v_add_f32_e32 v87, v87, v55
	v_add_f32_e32 v87, v87, v56
	v_add_f32_e32 v87, v87, v57
	v_and_or_b32 v22, v87, s54, v95
	s_waitcnt lgkmcnt(2)
	v_add_f32_e32 v88, v88, v58
	v_add_f32_e32 v88, v88, v59
	v_add_f32_e32 v88, v88, v60
	v_add_f32_e32 v88, v88, v61
	v_and_or_b32 v19, v88, s54, v94
	s_waitcnt lgkmcnt(0)
	v_add_f32_e32 v89, v89, v62
	v_add_f32_e32 v89, v89, v63
	v_add_f32_e32 v89, v89, v64
	v_add_f32_e32 v89, v89, v65
	v_and_or_b32 v23, v89, s54, v95
	ds_read_b32 v90, v97 offset:4096
	ds_read_b128 v[66:69], v96 offset:4096
	ds_read_b32 v91, v97 offset:5120
	ds_read_b128 v[70:73], v96 offset:5120
	ds_read_b32 v92, v97 offset:6144
	ds_read_b128 v[74:77], v96 offset:6144
	ds_read_b32 v93, v97 offset:7168
	ds_read_b128 v[78:81], v96 offset:7168
	s_waitcnt lgkmcnt(6)
	v_add_f32_e32 v90, v90, v66
	v_add_f32_e32 v90, v90, v67
	v_add_f32_e32 v90, v90, v68
	v_add_f32_e32 v90, v90, v69
	v_and_or_b32 v20, v90, s54, v94
	s_waitcnt lgkmcnt(4)
	v_add_f32_e32 v91, v91, v70
	v_add_f32_e32 v91, v91, v71
	v_add_f32_e32 v91, v91, v72
	v_add_f32_e32 v91, v91, v73
	v_and_or_b32 v24, v91, s54, v95
	s_waitcnt lgkmcnt(2)
	v_add_f32_e32 v92, v92, v74
	v_add_f32_e32 v92, v92, v75
	v_add_f32_e32 v92, v92, v76
	v_add_f32_e32 v92, v92, v77
	v_and_or_b32 v21, v92, s54, v94
	s_waitcnt lgkmcnt(0)
	v_add_f32_e32 v93, v93, v78
	v_add_f32_e32 v93, v93, v79
	v_add_f32_e32 v93, v93, v80
	v_add_f32_e32 v93, v93, v81
	v_and_or_b32 v25, v93, s54, v95
	v_cmp_le_i32_e64 s[14:15], v184, s21
	v_cmp_lt_i32_e64 s[34:35], 0, v184
	s_nop 0
	s_and_b64 s[14:15], s[14:15], s[34:35]
	v_cmp_le_i32_e64 s[34:35], v236, s21
	v_cndmask_b32_e64 v18, 0, v18, s[14:15]
	s_nop 0
	v_cndmask_b32_e64 v22, 0, v22, s[34:35]
	v_mov_b32_e32 v82, 127
	v_cndmask_b32_e64 v19, 0, v19, s[14:15]
	v_cndmask_b32_e64 v23, 0, v23, s[34:35]
	v_mov_b32_e32 v83, 127
	v_cndmask_b32_e64 v20, 0, v20, s[14:15]
	v_cndmask_b32_e64 v24, 0, v24, s[34:35]
	v_mov_b32_e32 v84, 127
	v_cndmask_b32_e64 v21, 0, v21, s[14:15]
	v_cndmask_b32_e64 v25, 0, v25, s[34:35]
	v_mov_b32_e32 v85, 127
	v_max_u32_e32 v26, v18, v22
	v_max_u32_e32 v27, v19, v23
	v_max_u32_e32 v28, v20, v24
	v_max_u32_e32 v29, v21, v25
	v_max_u32_dpp v26, v26, v26 quad_perm:[1,0,3,2] row_mask:0xf bank_mask:0xf
	v_max_u32_dpp v27, v27, v27 quad_perm:[1,0,3,2] row_mask:0xf bank_mask:0xf
	v_max_u32_dpp v28, v28, v28 quad_perm:[1,0,3,2] row_mask:0xf bank_mask:0xf
	v_max_u32_dpp v29, v29, v29 quad_perm:[1,0,3,2] row_mask:0xf bank_mask:0xf
	v_max_u32_dpp v26, v26, v26 quad_perm:[2,3,0,1] row_mask:0xf bank_mask:0xf
	v_max_u32_dpp v27, v27, v27 quad_perm:[2,3,0,1] row_mask:0xf bank_mask:0xf
	v_max_u32_dpp v28, v28, v28 quad_perm:[2,3,0,1] row_mask:0xf bank_mask:0xf
	v_max_u32_dpp v29, v29, v29 quad_perm:[2,3,0,1] row_mask:0xf bank_mask:0xf
	v_max_u32_dpp v26, v26, v26 row_half_mirror row_mask:0xf bank_mask:0xf
	v_max_u32_dpp v27, v27, v27 row_half_mirror row_mask:0xf bank_mask:0xf
	v_max_u32_dpp v28, v28, v28 row_half_mirror row_mask:0xf bank_mask:0xf
	v_max_u32_dpp v29, v29, v29 row_half_mirror row_mask:0xf bank_mask:0xf
	v_max_u32_dpp v26, v26, v26 row_mirror row_mask:0xf bank_mask:0xf
	v_max_u32_dpp v27, v27, v27 row_mirror row_mask:0xf bank_mask:0xf
; __device__ __forceinline__ void nsa_quad_pre(int bg, int quad, const bf16_t* Q, const bf16_t* KV, const bf16_t* KCMP, const bf16_t* VCMPT, const float* GN, bf16_t* ONSA, ...
;     ...
;             for (int it = 0; it < 13; ++it) {
;                 unsigned m = k0 > k1 ? k0 : k1;
; #pragma unroll
;                 for (int off = 32; off >= 1; off >>= 1) { const unsigned o = (unsigned)__shfl_xor((int)m, off); m = o > m ? o : m; }
;                 if (k0 == m) k0 = 0u; if (k1 == m) k1 = 0u;
;                 if (lane == 0) selq[tt * 16 + it] = 127 - (int)(m & 127u);
;             }
	v_max_u32_dpp v28, v28, v28 row_mirror row_mask:0xf bank_mask:0xf
	v_max_u32_dpp v29, v29, v29 row_mirror row_mask:0xf bank_mask:0xf
	v_max_u32_dpp v26, v26, v26 row_bcast:15 row_mask:0xa bank_mask:0xf
	v_max_u32_dpp v27, v27, v27 row_bcast:15 row_mask:0xa bank_mask:0xf
	v_max_u32_dpp v28, v28, v28 row_bcast:15 row_mask:0xa bank_mask:0xf
	v_max_u32_dpp v29, v29, v29 row_bcast:15 row_mask:0xa bank_mask:0xf
	v_max_u32_dpp v26, v26, v26 row_bcast:31 row_mask:0xc bank_mask:0xf
	v_max_u32_dpp v27, v27, v27 row_bcast:31 row_mask:0xc bank_mask:0xf
	v_max_u32_dpp v28, v28, v28 row_bcast:31 row_mask:0xc bank_mask:0xf
	v_max_u32_dpp v29, v29, v29 row_bcast:31 row_mask:0xc bank_mask:0xf
	v_readlane_b32 s14, v26, 63
	v_readlane_b32 s15, v27, 63
	v_readlane_b32 s34, v28, 63
	v_readlane_b32 s35, v29, 63
	v_writelane_b32 v82, s14, 0
	v_writelane_b32 v83, s15, 0
	v_writelane_b32 v84, s34, 0
	v_writelane_b32 v85, s35, 0
	v_cmp_ne_u32_e64 s[42:43], s14, v18
	v_cmp_ne_u32_e64 s[66:67], s14, v22
	v_cmp_ne_u32_e64 s[0:1], s15, v19
	v_cmp_ne_u32_e32 vcc, s15, v23
	v_cndmask_b32_e64 v18, 0, v18, s[42:43]
	v_cndmask_b32_e64 v22, 0, v22, s[66:67]
	v_cndmask_b32_e64 v19, 0, v19, s[0:1]
	v_cndmask_b32_e32 v23, 0, v23, vcc
	v_cmp_ne_u32_e64 s[42:43], s34, v20
	v_cmp_ne_u32_e64 s[66:67], s34, v24
	v_cmp_ne_u32_e64 s[0:1], s35, v21
	v_cmp_ne_u32_e32 vcc, s35, v25
	v_cndmask_b32_e64 v20, 0, v20, s[42:43]
	v_cndmask_b32_e64 v24, 0, v24, s[66:67]
	v_cndmask_b32_e64 v21, 0, v21, s[0:1]
	v_cndmask_b32_e32 v25, 0, v25, vcc
	v_max_u32_e32 v26, v18, v22
	v_max_u32_e32 v27, v19, v23
	v_max_u32_e32 v28, v20, v24
	v_max_u32_e32 v29, v21, v25
	v_max_u32_dpp v26, v26, v26 quad_perm:[1,0,3,2] row_mask:0xf bank_mask:0xf
	v_max_u32_dpp v27, v27, v27 quad_perm:[1,0,3,2] row_mask:0xf bank_mask:0xf
	v_max_u32_dpp v28, v28, v28 quad_perm:[1,0,3,2] row_mask:0xf bank_mask:0xf
	v_max_u32_dpp v29, v29, v29 quad_perm:[1,0,3,2] row_mask:0xf bank_mask:0xf
	v_max_u32_dpp v26, v26, v26 quad_perm:[2,3,0,1] row_mask:0xf bank_mask:0xf
	v_max_u32_dpp v27, v27, v27 quad_perm:[2,3,0,1] row_mask:0xf bank_mask:0xf
	v_max_u32_dpp v28, v28, v28 quad_perm:[2,3,0,1] row_mask:0xf bank_mask:0xf
	v_max_u32_dpp v29, v29, v29 quad_perm:[2,3,0,1] row_mask:0xf bank_mask:0xf
	v_max_u32_dpp v26, v26, v26 row_half_mirror row_mask:0xf bank_mask:0xf
	v_max_u32_dpp v27, v27, v27 row_half_mirror row_mask:0xf bank_mask:0xf
	v_max_u32_dpp v28, v28, v28 row_half_mirror row_mask:0xf bank_mask:0xf
	v_max_u32_dpp v29, v29, v29 row_half_mirror row_mask:0xf bank_mask:0xf
	v_max_u32_dpp v26, v26, v26 row_mirror row_mask:0xf bank_mask:0xf
	v_max_u32_dpp v27, v27, v27 row_mirror row_mask:0xf bank_mask:0xf
	v_max_u32_dpp v28, v28, v28 row_mirror row_mask:0xf bank_mask:0xf
	v_max_u32_dpp v29, v29, v29 row_mirror row_mask:0xf bank_mask:0xf
	v_max_u32_dpp v26, v26, v26 row_bcast:15 row_mask:0xa bank_mask:0xf
	v_max_u32_dpp v27, v27, v27 row_bcast:15 row_mask:0xa bank_mask:0xf
	v_max_u32_dpp v28, v28, v28 row_bcast:15 row_mask:0xa bank_mask:0xf
	v_max_u32_dpp v29, v29, v29 row_bcast:15 row_mask:0xa bank_mask:0xf
	v_max_u32_dpp v26, v26, v26 row_bcast:31 row_mask:0xc bank_mask:0xf
	v_max_u32_dpp v27, v27, v27 row_bcast:31 row_mask:0xc bank_mask:0xf
	v_max_u32_dpp v28, v28, v28 row_bcast:31 row_mask:0xc bank_mask:0xf
	v_max_u32_dpp v29, v29, v29 row_bcast:31 row_mask:0xc bank_mask:0xf
	v_readlane_b32 s14, v26, 63
	v_readlane_b32 s15, v27, 63
	v_readlane_b32 s34, v28, 63
	v_readlane_b32 s35, v29, 63
	v_writelane_b32 v82, s14, 1
	v_writelane_b32 v83, s15, 1
	v_writelane_b32 v84, s34, 1
	v_writelane_b32 v85, s35, 1
	v_cmp_ne_u32_e64 s[42:43], s14, v18
	v_cmp_ne_u32_e64 s[66:67], s14, v22
	v_cmp_ne_u32_e64 s[0:1], s15, v19
	v_cmp_ne_u32_e32 vcc, s15, v23
	v_cndmask_b32_e64 v18, 0, v18, s[42:43]
	v_cndmask_b32_e64 v22, 0, v22, s[66:67]
	v_cndmask_b32_e64 v19, 0, v19, s[0:1]
	v_cndmask_b32_e32 v23, 0, v23, vcc
	v_cmp_ne_u32_e64 s[42:43], s34, v20
	v_cmp_ne_u32_e64 s[66:67], s34, v24
	v_cmp_ne_u32_e64 s[0:1], s35, v21
	v_cmp_ne_u32_e32 vcc, s35, v25
	v_cndmask_b32_e64 v20, 0, v20, s[42:43]
	v_cndmask_b32_e64 v24, 0, v24, s[66:67]
	v_cndmask_b32_e64 v21, 0, v21, s[0:1]
	v_cndmask_b32_e32 v25, 0, v25, vcc
	v_max_u32_e32 v26, v18, v22
	v_max_u32_e32 v27, v19, v23
	v_max_u32_e32 v28, v20, v24
	v_max_u32_e32 v29, v21, v25
	v_max_u32_dpp v26, v26, v26 quad_perm:[1,0,3,2] row_mask:0xf bank_mask:0xf
	v_max_u32_dpp v27, v27, v27 quad_perm:[1,0,3,2] row_mask:0xf bank_mask:0xf
	v_max_u32_dpp v28, v28, v28 quad_perm:[1,0,3,2] row_mask:0xf bank_mask:0xf
	v_max_u32_dpp v29, v29, v29 quad_perm:[1,0,3,2] row_mask:0xf bank_mask:0xf
	v_max_u32_dpp v26, v26, v26 quad_perm:[2,3,0,1] row_mask:0xf bank_mask:0xf
	v_max_u32_dpp v27, v27, v27 quad_perm:[2,3,0,1] row_mask:0xf bank_mask:0xf
	v_max_u32_dpp v28, v28, v28 quad_perm:[2,3,0,1] row_mask:0xf bank_mask:0xf
	v_max_u32_dpp v29, v29, v29 quad_perm:[2,3,0,1] row_mask:0xf bank_mask:0xf
	v_max_u32_dpp v26, v26, v26 row_half_mirror row_mask:0xf bank_mask:0xf
	v_max_u32_dpp v27, v27, v27 row_half_mirror row_mask:0xf bank_mask:0xf
	v_max_u32_dpp v28, v28, v28 row_half_mirror row_mask:0xf bank_mask:0xf
	v_max_u32_dpp v29, v29, v29 row_half_mirror row_mask:0xf bank_mask:0xf
	v_max_u32_dpp v26, v26, v26 row_mirror row_mask:0xf bank_mask:0xf
	v_max_u32_dpp v27, v27, v27 row_mirror row_mask:0xf bank_mask:0xf
	v_max_u32_dpp v28, v28, v28 row_mirror row_mask:0xf bank_mask:0xf
	v_max_u32_dpp v29, v29, v29 row_mirror row_mask:0xf bank_mask:0xf
	v_max_u32_dpp v26, v26, v26 row_bcast:15 row_mask:0xa bank_mask:0xf
	v_max_u32_dpp v27, v27, v27 row_bcast:15 row_mask:0xa bank_mask:0xf
	v_max_u32_dpp v28, v28, v28 row_bcast:15 row_mask:0xa bank_mask:0xf
; __device__ __forceinline__ void nsa_quad_pre(int bg, int quad, const bf16_t* Q, const bf16_t* KV, const bf16_t* KCMP, const bf16_t* VCMPT, const float* GN, bf16_t* ONSA, ...
;     ...
;             for (int it = 0; it < 13; ++it) {
;                 unsigned m = k0 > k1 ? k0 : k1;
; #pragma unroll
;                 for (int off = 32; off >= 1; off >>= 1) { const unsigned o = (unsigned)__shfl_xor((int)m, off); m = o > m ? o : m; }
;                 if (k0 == m) k0 = 0u; if (k1 == m) k1 = 0u;
;                 if (lane == 0) selq[tt * 16 + it] = 127 - (int)(m & 127u);
;             }
	v_max_u32_dpp v29, v29, v29 row_bcast:15 row_mask:0xa bank_mask:0xf
	v_max_u32_dpp v26, v26, v26 row_bcast:31 row_mask:0xc bank_mask:0xf
	v_max_u32_dpp v27, v27, v27 row_bcast:31 row_mask:0xc bank_mask:0xf
	v_max_u32_dpp v28, v28, v28 row_bcast:31 row_mask:0xc bank_mask:0xf
	v_max_u32_dpp v29, v29, v29 row_bcast:31 row_mask:0xc bank_mask:0xf
	v_readlane_b32 s14, v26, 63
	v_readlane_b32 s15, v27, 63
	v_readlane_b32 s34, v28, 63
	v_readlane_b32 s35, v29, 63
	v_writelane_b32 v82, s14, 2
	v_writelane_b32 v83, s15, 2
	v_writelane_b32 v84, s34, 2
	v_writelane_b32 v85, s35, 2
	v_cmp_ne_u32_e64 s[42:43], s14, v18
	v_cmp_ne_u32_e64 s[66:67], s14, v22
	v_cmp_ne_u32_e64 s[0:1], s15, v19
	v_cmp_ne_u32_e32 vcc, s15, v23
	v_cndmask_b32_e64 v18, 0, v18, s[42:43]
	v_cndmask_b32_e64 v22, 0, v22, s[66:67]
	v_cndmask_b32_e64 v19, 0, v19, s[0:1]
	v_cndmask_b32_e32 v23, 0, v23, vcc
	v_cmp_ne_u32_e64 s[42:43], s34, v20
	v_cmp_ne_u32_e64 s[66:67], s34, v24
	v_cmp_ne_u32_e64 s[0:1], s35, v21
	v_cmp_ne_u32_e32 vcc, s35, v25
	v_cndmask_b32_e64 v20, 0, v20, s[42:43]
	v_cndmask_b32_e64 v24, 0, v24, s[66:67]
	v_cndmask_b32_e64 v21, 0, v21, s[0:1]
	v_cndmask_b32_e32 v25, 0, v25, vcc
	v_max_u32_e32 v26, v18, v22
	v_max_u32_e32 v27, v19, v23
	v_max_u32_e32 v28, v20, v24
	v_max_u32_e32 v29, v21, v25
	v_max_u32_dpp v26, v26, v26 quad_perm:[1,0,3,2] row_mask:0xf bank_mask:0xf
	v_max_u32_dpp v27, v27, v27 quad_perm:[1,0,3,2] row_mask:0xf bank_mask:0xf
	v_max_u32_dpp v28, v28, v28 quad_perm:[1,0,3,2] row_mask:0xf bank_mask:0xf
	v_max_u32_dpp v29, v29, v29 quad_perm:[1,0,3,2] row_mask:0xf bank_mask:0xf
	v_max_u32_dpp v26, v26, v26 quad_perm:[2,3,0,1] row_mask:0xf bank_mask:0xf
	v_max_u32_dpp v27, v27, v27 quad_perm:[2,3,0,1] row_mask:0xf bank_mask:0xf
	v_max_u32_dpp v28, v28, v28 quad_perm:[2,3,0,1] row_mask:0xf bank_mask:0xf
	v_max_u32_dpp v29, v29, v29 quad_perm:[2,3,0,1] row_mask:0xf bank_mask:0xf
	v_max_u32_dpp v26, v26, v26 row_half_mirror row_mask:0xf bank_mask:0xf
	v_max_u32_dpp v27, v27, v27 row_half_mirror row_mask:0xf bank_mask:0xf
	v_max_u32_dpp v28, v28, v28 row_half_mirror row_mask:0xf bank_mask:0xf
	v_max_u32_dpp v29, v29, v29 row_half_mirror row_mask:0xf bank_mask:0xf
	v_max_u32_dpp v26, v26, v26 row_mirror row_mask:0xf bank_mask:0xf
	v_max_u32_dpp v27, v27, v27 row_mirror row_mask:0xf bank_mask:0xf
	v_max_u32_dpp v28, v28, v28 row_mirror row_mask:0xf bank_mask:0xf
	v_max_u32_dpp v29, v29, v29 row_mirror row_mask:0xf bank_mask:0xf
	v_max_u32_dpp v26, v26, v26 row_bcast:15 row_mask:0xa bank_mask:0xf
	v_max_u32_dpp v27, v27, v27 row_bcast:15 row_mask:0xa bank_mask:0xf
	v_max_u32_dpp v28, v28, v28 row_bcast:15 row_mask:0xa bank_mask:0xf
	v_max_u32_dpp v29, v29, v29 row_bcast:15 row_mask:0xa bank_mask:0xf
	v_max_u32_dpp v26, v26, v26 row_bcast:31 row_mask:0xc bank_mask:0xf
	v_max_u32_dpp v27, v27, v27 row_bcast:31 row_mask:0xc bank_mask:0xf
	v_max_u32_dpp v28, v28, v28 row_bcast:31 row_mask:0xc bank_mask:0xf
	v_max_u32_dpp v29, v29, v29 row_bcast:31 row_mask:0xc bank_mask:0xf
	v_readlane_b32 s14, v26, 63
	v_readlane_b32 s15, v27, 63
	v_readlane_b32 s34, v28, 63
	v_readlane_b32 s35, v29, 63
	v_writelane_b32 v82, s14, 3
	v_writelane_b32 v83, s15, 3
	v_writelane_b32 v84, s34, 3
	v_writelane_b32 v85, s35, 3
	v_cmp_ne_u32_e64 s[42:43], s14, v18
	v_cmp_ne_u32_e64 s[66:67], s14, v22
	v_cmp_ne_u32_e64 s[0:1], s15, v19
	v_cmp_ne_u32_e32 vcc, s15, v23
	v_cndmask_b32_e64 v18, 0, v18, s[42:43]
	v_cndmask_b32_e64 v22, 0, v22, s[66:67]
	v_cndmask_b32_e64 v19, 0, v19, s[0:1]
	v_cndmask_b32_e32 v23, 0, v23, vcc
	v_cmp_ne_u32_e64 s[42:43], s34, v20
	v_cmp_ne_u32_e64 s[66:67], s34, v24
	v_cmp_ne_u32_e64 s[0:1], s35, v21
	v_cmp_ne_u32_e32 vcc, s35, v25
	v_cndmask_b32_e64 v20, 0, v20, s[42:43]
	v_cndmask_b32_e64 v24, 0, v24, s[66:67]
	v_cndmask_b32_e64 v21, 0, v21, s[0:1]
	v_cndmask_b32_e32 v25, 0, v25, vcc
	v_max_u32_e32 v26, v18, v22
	v_max_u32_e32 v27, v19, v23
	v_max_u32_e32 v28, v20, v24
	v_max_u32_e32 v29, v21, v25
	v_max_u32_dpp v26, v26, v26 quad_perm:[1,0,3,2] row_mask:0xf bank_mask:0xf
	v_max_u32_dpp v27, v27, v27 quad_perm:[1,0,3,2] row_mask:0xf bank_mask:0xf
	v_max_u32_dpp v28, v28, v28 quad_perm:[1,0,3,2] row_mask:0xf bank_mask:0xf
	v_max_u32_dpp v29, v29, v29 quad_perm:[1,0,3,2] row_mask:0xf bank_mask:0xf
	v_max_u32_dpp v26, v26, v26 quad_perm:[2,3,0,1] row_mask:0xf bank_mask:0xf
	v_max_u32_dpp v27, v27, v27 quad_perm:[2,3,0,1] row_mask:0xf bank_mask:0xf
	v_max_u32_dpp v28, v28, v28 quad_perm:[2,3,0,1] row_mask:0xf bank_mask:0xf
	v_max_u32_dpp v29, v29, v29 quad_perm:[2,3,0,1] row_mask:0xf bank_mask:0xf
	v_max_u32_dpp v26, v26, v26 row_half_mirror row_mask:0xf bank_mask:0xf
	v_max_u32_dpp v27, v27, v27 row_half_mirror row_mask:0xf bank_mask:0xf
	v_max_u32_dpp v28, v28, v28 row_half_mirror row_mask:0xf bank_mask:0xf
	v_max_u32_dpp v29, v29, v29 row_half_mirror row_mask:0xf bank_mask:0xf
	v_max_u32_dpp v26, v26, v26 row_mirror row_mask:0xf bank_mask:0xf
	v_max_u32_dpp v27, v27, v27 row_mirror row_mask:0xf bank_mask:0xf
	v_max_u32_dpp v28, v28, v28 row_mirror row_mask:0xf bank_mask:0xf
	v_max_u32_dpp v29, v29, v29 row_mirror row_mask:0xf bank_mask:0xf
	v_max_u32_dpp v26, v26, v26 row_bcast:15 row_mask:0xa bank_mask:0xf
	v_max_u32_dpp v27, v27, v27 row_bcast:15 row_mask:0xa bank_mask:0xf
	v_max_u32_dpp v28, v28, v28 row_bcast:15 row_mask:0xa bank_mask:0xf
	v_max_u32_dpp v29, v29, v29 row_bcast:15 row_mask:0xa bank_mask:0xf
	v_max_u32_dpp v26, v26, v26 row_bcast:31 row_mask:0xc bank_mask:0xf
	v_max_u32_dpp v27, v27, v27 row_bcast:31 row_mask:0xc bank_mask:0xf
	v_max_u32_dpp v28, v28, v28 row_bcast:31 row_mask:0xc bank_mask:0xf
	v_max_u32_dpp v29, v29, v29 row_bcast:31 row_mask:0xc bank_mask:0xf
; __device__ __forceinline__ void nsa_quad_pre(int bg, int quad, const bf16_t* Q, const bf16_t* KV, const bf16_t* KCMP, const bf16_t* VCMPT, const float* GN, bf16_t* ONSA, ...
;     ...
;             for (int it = 0; it < 13; ++it) {
;                 unsigned m = k0 > k1 ? k0 : k1;
; #pragma unroll
;                 for (int off = 32; off >= 1; off >>= 1) { const unsigned o = (unsigned)__shfl_xor((int)m, off); m = o > m ? o : m; }
;                 if (k0 == m) k0 = 0u; if (k1 == m) k1 = 0u;
;                 if (lane == 0) selq[tt * 16 + it] = 127 - (int)(m & 127u);
;             }
	v_readlane_b32 s14, v26, 63
	v_readlane_b32 s15, v27, 63
	v_readlane_b32 s34, v28, 63
	v_readlane_b32 s35, v29, 63
	v_writelane_b32 v82, s14, 4
	v_writelane_b32 v83, s15, 4
	v_writelane_b32 v84, s34, 4
	v_writelane_b32 v85, s35, 4
	v_cmp_ne_u32_e64 s[42:43], s14, v18
	v_cmp_ne_u32_e64 s[66:67], s14, v22
	v_cmp_ne_u32_e64 s[0:1], s15, v19
	v_cmp_ne_u32_e32 vcc, s15, v23
	v_cndmask_b32_e64 v18, 0, v18, s[42:43]
	v_cndmask_b32_e64 v22, 0, v22, s[66:67]
	v_cndmask_b32_e64 v19, 0, v19, s[0:1]
	v_cndmask_b32_e32 v23, 0, v23, vcc
	v_cmp_ne_u32_e64 s[42:43], s34, v20
	v_cmp_ne_u32_e64 s[66:67], s34, v24
	v_cmp_ne_u32_e64 s[0:1], s35, v21
	v_cmp_ne_u32_e32 vcc, s35, v25
	v_cndmask_b32_e64 v20, 0, v20, s[42:43]
	v_cndmask_b32_e64 v24, 0, v24, s[66:67]
	v_cndmask_b32_e64 v21, 0, v21, s[0:1]
	v_cndmask_b32_e32 v25, 0, v25, vcc
	v_max_u32_e32 v26, v18, v22
	v_max_u32_e32 v27, v19, v23
	v_max_u32_e32 v28, v20, v24
	v_max_u32_e32 v29, v21, v25
	v_max_u32_dpp v26, v26, v26 quad_perm:[1,0,3,2] row_mask:0xf bank_mask:0xf
	v_max_u32_dpp v27, v27, v27 quad_perm:[1,0,3,2] row_mask:0xf bank_mask:0xf
	v_max_u32_dpp v28, v28, v28 quad_perm:[1,0,3,2] row_mask:0xf bank_mask:0xf
	v_max_u32_dpp v29, v29, v29 quad_perm:[1,0,3,2] row_mask:0xf bank_mask:0xf
	v_max_u32_dpp v26, v26, v26 quad_perm:[2,3,0,1] row_mask:0xf bank_mask:0xf
	v_max_u32_dpp v27, v27, v27 quad_perm:[2,3,0,1] row_mask:0xf bank_mask:0xf
	v_max_u32_dpp v28, v28, v28 quad_perm:[2,3,0,1] row_mask:0xf bank_mask:0xf
	v_max_u32_dpp v29, v29, v29 quad_perm:[2,3,0,1] row_mask:0xf bank_mask:0xf
	v_max_u32_dpp v26, v26, v26 row_half_mirror row_mask:0xf bank_mask:0xf
	v_max_u32_dpp v27, v27, v27 row_half_mirror row_mask:0xf bank_mask:0xf
	v_max_u32_dpp v28, v28, v28 row_half_mirror row_mask:0xf bank_mask:0xf
	v_max_u32_dpp v29, v29, v29 row_half_mirror row_mask:0xf bank_mask:0xf
	v_max_u32_dpp v26, v26, v26 row_mirror row_mask:0xf bank_mask:0xf
	v_max_u32_dpp v27, v27, v27 row_mirror row_mask:0xf bank_mask:0xf
	v_max_u32_dpp v28, v28, v28 row_mirror row_mask:0xf bank_mask:0xf
	v_max_u32_dpp v29, v29, v29 row_mirror row_mask:0xf bank_mask:0xf
	v_max_u32_dpp v26, v26, v26 row_bcast:15 row_mask:0xa bank_mask:0xf
	v_max_u32_dpp v27, v27, v27 row_bcast:15 row_mask:0xa bank_mask:0xf
	v_max_u32_dpp v28, v28, v28 row_bcast:15 row_mask:0xa bank_mask:0xf
	v_max_u32_dpp v29, v29, v29 row_bcast:15 row_mask:0xa bank_mask:0xf
	v_max_u32_dpp v26, v26, v26 row_bcast:31 row_mask:0xc bank_mask:0xf
	v_max_u32_dpp v27, v27, v27 row_bcast:31 row_mask:0xc bank_mask:0xf
	v_max_u32_dpp v28, v28, v28 row_bcast:31 row_mask:0xc bank_mask:0xf
	v_max_u32_dpp v29, v29, v29 row_bcast:31 row_mask:0xc bank_mask:0xf
	v_readlane_b32 s14, v26, 63
	v_readlane_b32 s15, v27, 63
	v_readlane_b32 s34, v28, 63
	v_readlane_b32 s35, v29, 63
	v_writelane_b32 v82, s14, 5
	v_writelane_b32 v83, s15, 5
	v_writelane_b32 v84, s34, 5
	v_writelane_b32 v85, s35, 5
	v_cmp_ne_u32_e64 s[42:43], s14, v18
	v_cmp_ne_u32_e64 s[66:67], s14, v22
	v_cmp_ne_u32_e64 s[0:1], s15, v19
	v_cmp_ne_u32_e32 vcc, s15, v23
	v_cndmask_b32_e64 v18, 0, v18, s[42:43]
	v_cndmask_b32_e64 v22, 0, v22, s[66:67]
	v_cndmask_b32_e64 v19, 0, v19, s[0:1]
	v_cndmask_b32_e32 v23, 0, v23, vcc
	v_cmp_ne_u32_e64 s[42:43], s34, v20
	v_cmp_ne_u32_e64 s[66:67], s34, v24
	v_cmp_ne_u32_e64 s[0:1], s35, v21
	v_cmp_ne_u32_e32 vcc, s35, v25
	v_cndmask_b32_e64 v20, 0, v20, s[42:43]
	v_cndmask_b32_e64 v24, 0, v24, s[66:67]
	v_cndmask_b32_e64 v21, 0, v21, s[0:1]
	v_cndmask_b32_e32 v25, 0, v25, vcc
	v_max_u32_e32 v26, v18, v22
	v_max_u32_e32 v27, v19, v23
	v_max_u32_e32 v28, v20, v24
	v_max_u32_e32 v29, v21, v25
	v_max_u32_dpp v26, v26, v26 quad_perm:[1,0,3,2] row_mask:0xf bank_mask:0xf
	v_max_u32_dpp v27, v27, v27 quad_perm:[1,0,3,2] row_mask:0xf bank_mask:0xf
	v_max_u32_dpp v28, v28, v28 quad_perm:[1,0,3,2] row_mask:0xf bank_mask:0xf
	v_max_u32_dpp v29, v29, v29 quad_perm:[1,0,3,2] row_mask:0xf bank_mask:0xf
	v_max_u32_dpp v26, v26, v26 quad_perm:[2,3,0,1] row_mask:0xf bank_mask:0xf
	v_max_u32_dpp v27, v27, v27 quad_perm:[2,3,0,1] row_mask:0xf bank_mask:0xf
	v_max_u32_dpp v28, v28, v28 quad_perm:[2,3,0,1] row_mask:0xf bank_mask:0xf
	v_max_u32_dpp v29, v29, v29 quad_perm:[2,3,0,1] row_mask:0xf bank_mask:0xf
	v_max_u32_dpp v26, v26, v26 row_half_mirror row_mask:0xf bank_mask:0xf
	v_max_u32_dpp v27, v27, v27 row_half_mirror row_mask:0xf bank_mask:0xf
	v_max_u32_dpp v28, v28, v28 row_half_mirror row_mask:0xf bank_mask:0xf
	v_max_u32_dpp v29, v29, v29 row_half_mirror row_mask:0xf bank_mask:0xf
	v_max_u32_dpp v26, v26, v26 row_mirror row_mask:0xf bank_mask:0xf
	v_max_u32_dpp v27, v27, v27 row_mirror row_mask:0xf bank_mask:0xf
	v_max_u32_dpp v28, v28, v28 row_mirror row_mask:0xf bank_mask:0xf
	v_max_u32_dpp v29, v29, v29 row_mirror row_mask:0xf bank_mask:0xf
	v_max_u32_dpp v26, v26, v26 row_bcast:15 row_mask:0xa bank_mask:0xf
	v_max_u32_dpp v27, v27, v27 row_bcast:15 row_mask:0xa bank_mask:0xf
	v_max_u32_dpp v28, v28, v28 row_bcast:15 row_mask:0xa bank_mask:0xf
	v_max_u32_dpp v29, v29, v29 row_bcast:15 row_mask:0xa bank_mask:0xf
	v_max_u32_dpp v26, v26, v26 row_bcast:31 row_mask:0xc bank_mask:0xf
	v_max_u32_dpp v27, v27, v27 row_bcast:31 row_mask:0xc bank_mask:0xf
	v_max_u32_dpp v28, v28, v28 row_bcast:31 row_mask:0xc bank_mask:0xf
	v_max_u32_dpp v29, v29, v29 row_bcast:31 row_mask:0xc bank_mask:0xf
	v_readlane_b32 s14, v26, 63
	v_readlane_b32 s15, v27, 63
	v_readlane_b32 s34, v28, 63
	v_readlane_b32 s35, v29, 63
	v_writelane_b32 v82, s14, 6
	v_writelane_b32 v83, s15, 6
	v_writelane_b32 v84, s34, 6
	v_writelane_b32 v85, s35, 6
	v_cmp_ne_u32_e64 s[42:43], s14, v18
	v_cmp_ne_u32_e64 s[66:67], s14, v22
; __device__ __forceinline__ void nsa_quad_pre(int bg, int quad, const bf16_t* Q, const bf16_t* KV, const bf16_t* KCMP, const bf16_t* VCMPT, const float* GN, bf16_t* ONSA, ...
;     ...
;             for (int it = 0; it < 13; ++it) {
;                 unsigned m = k0 > k1 ? k0 : k1;
; #pragma unroll
;                 for (int off = 32; off >= 1; off >>= 1) { const unsigned o = (unsigned)__shfl_xor((int)m, off); m = o > m ? o : m; }
;                 if (k0 == m) k0 = 0u; if (k1 == m) k1 = 0u;
;                 if (lane == 0) selq[tt * 16 + it] = 127 - (int)(m & 127u);
;             }
	v_cmp_ne_u32_e64 s[0:1], s15, v19
	v_cmp_ne_u32_e32 vcc, s15, v23
	v_cndmask_b32_e64 v18, 0, v18, s[42:43]
	v_cndmask_b32_e64 v22, 0, v22, s[66:67]
	v_cndmask_b32_e64 v19, 0, v19, s[0:1]
	v_cndmask_b32_e32 v23, 0, v23, vcc
	v_cmp_ne_u32_e64 s[42:43], s34, v20
	v_cmp_ne_u32_e64 s[66:67], s34, v24
	v_cmp_ne_u32_e64 s[0:1], s35, v21
	v_cmp_ne_u32_e32 vcc, s35, v25
	v_cndmask_b32_e64 v20, 0, v20, s[42:43]
	v_cndmask_b32_e64 v24, 0, v24, s[66:67]
	v_cndmask_b32_e64 v21, 0, v21, s[0:1]
	v_cndmask_b32_e32 v25, 0, v25, vcc
	v_max_u32_e32 v26, v18, v22
	v_max_u32_e32 v27, v19, v23
	v_max_u32_e32 v28, v20, v24
	v_max_u32_e32 v29, v21, v25
	v_max_u32_dpp v26, v26, v26 quad_perm:[1,0,3,2] row_mask:0xf bank_mask:0xf
	v_max_u32_dpp v27, v27, v27 quad_perm:[1,0,3,2] row_mask:0xf bank_mask:0xf
	v_max_u32_dpp v28, v28, v28 quad_perm:[1,0,3,2] row_mask:0xf bank_mask:0xf
	v_max_u32_dpp v29, v29, v29 quad_perm:[1,0,3,2] row_mask:0xf bank_mask:0xf
	v_max_u32_dpp v26, v26, v26 quad_perm:[2,3,0,1] row_mask:0xf bank_mask:0xf
	v_max_u32_dpp v27, v27, v27 quad_perm:[2,3,0,1] row_mask:0xf bank_mask:0xf
	v_max_u32_dpp v28, v28, v28 quad_perm:[2,3,0,1] row_mask:0xf bank_mask:0xf
	v_max_u32_dpp v29, v29, v29 quad_perm:[2,3,0,1] row_mask:0xf bank_mask:0xf
	v_max_u32_dpp v26, v26, v26 row_half_mirror row_mask:0xf bank_mask:0xf
	v_max_u32_dpp v27, v27, v27 row_half_mirror row_mask:0xf bank_mask:0xf
	v_max_u32_dpp v28, v28, v28 row_half_mirror row_mask:0xf bank_mask:0xf
	v_max_u32_dpp v29, v29, v29 row_half_mirror row_mask:0xf bank_mask:0xf
	v_max_u32_dpp v26, v26, v26 row_mirror row_mask:0xf bank_mask:0xf
	v_max_u32_dpp v27, v27, v27 row_mirror row_mask:0xf bank_mask:0xf
	v_max_u32_dpp v28, v28, v28 row_mirror row_mask:0xf bank_mask:0xf
	v_max_u32_dpp v29, v29, v29 row_mirror row_mask:0xf bank_mask:0xf
	v_max_u32_dpp v26, v26, v26 row_bcast:15 row_mask:0xa bank_mask:0xf
	v_max_u32_dpp v27, v27, v27 row_bcast:15 row_mask:0xa bank_mask:0xf
	v_max_u32_dpp v28, v28, v28 row_bcast:15 row_mask:0xa bank_mask:0xf
	v_max_u32_dpp v29, v29, v29 row_bcast:15 row_mask:0xa bank_mask:0xf
	v_max_u32_dpp v26, v26, v26 row_bcast:31 row_mask:0xc bank_mask:0xf
	v_max_u32_dpp v27, v27, v27 row_bcast:31 row_mask:0xc bank_mask:0xf
	v_max_u32_dpp v28, v28, v28 row_bcast:31 row_mask:0xc bank_mask:0xf
	v_max_u32_dpp v29, v29, v29 row_bcast:31 row_mask:0xc bank_mask:0xf
	v_readlane_b32 s14, v26, 63
	v_readlane_b32 s15, v27, 63
	v_readlane_b32 s34, v28, 63
	v_readlane_b32 s35, v29, 63
	v_writelane_b32 v82, s14, 7
	v_writelane_b32 v83, s15, 7
	v_writelane_b32 v84, s34, 7
	v_writelane_b32 v85, s35, 7
	v_cmp_ne_u32_e64 s[42:43], s14, v18
	v_cmp_ne_u32_e64 s[66:67], s14, v22
	v_cmp_ne_u32_e64 s[0:1], s15, v19
	v_cmp_ne_u32_e32 vcc, s15, v23
	v_cndmask_b32_e64 v18, 0, v18, s[42:43]
	v_cndmask_b32_e64 v22, 0, v22, s[66:67]
	v_cndmask_b32_e64 v19, 0, v19, s[0:1]
	v_cndmask_b32_e32 v23, 0, v23, vcc
	v_cmp_ne_u32_e64 s[42:43], s34, v20
	v_cmp_ne_u32_e64 s[66:67], s34, v24
	v_cmp_ne_u32_e64 s[0:1], s35, v21
	v_cmp_ne_u32_e32 vcc, s35, v25
	v_cndmask_b32_e64 v20, 0, v20, s[42:43]
	v_cndmask_b32_e64 v24, 0, v24, s[66:67]
	v_cndmask_b32_e64 v21, 0, v21, s[0:1]
	v_cndmask_b32_e32 v25, 0, v25, vcc
	v_max_u32_e32 v26, v18, v22
	v_max_u32_e32 v27, v19, v23
	v_max_u32_e32 v28, v20, v24
	v_max_u32_e32 v29, v21, v25
	v_max_u32_dpp v26, v26, v26 quad_perm:[1,0,3,2] row_mask:0xf bank_mask:0xf
	v_max_u32_dpp v27, v27, v27 quad_perm:[1,0,3,2] row_mask:0xf bank_mask:0xf
	v_max_u32_dpp v28, v28, v28 quad_perm:[1,0,3,2] row_mask:0xf bank_mask:0xf
	v_max_u32_dpp v29, v29, v29 quad_perm:[1,0,3,2] row_mask:0xf bank_mask:0xf
	v_max_u32_dpp v26, v26, v26 quad_perm:[2,3,0,1] row_mask:0xf bank_mask:0xf
	v_max_u32_dpp v27, v27, v27 quad_perm:[2,3,0,1] row_mask:0xf bank_mask:0xf
	v_max_u32_dpp v28, v28, v28 quad_perm:[2,3,0,1] row_mask:0xf bank_mask:0xf
	v_max_u32_dpp v29, v29, v29 quad_perm:[2,3,0,1] row_mask:0xf bank_mask:0xf
	v_max_u32_dpp v26, v26, v26 row_half_mirror row_mask:0xf bank_mask:0xf
	v_max_u32_dpp v27, v27, v27 row_half_mirror row_mask:0xf bank_mask:0xf
	v_max_u32_dpp v28, v28, v28 row_half_mirror row_mask:0xf bank_mask:0xf
	v_max_u32_dpp v29, v29, v29 row_half_mirror row_mask:0xf bank_mask:0xf
	v_max_u32_dpp v26, v26, v26 row_mirror row_mask:0xf bank_mask:0xf
	v_max_u32_dpp v27, v27, v27 row_mirror row_mask:0xf bank_mask:0xf
	v_max_u32_dpp v28, v28, v28 row_mirror row_mask:0xf bank_mask:0xf
	v_max_u32_dpp v29, v29, v29 row_mirror row_mask:0xf bank_mask:0xf
	v_max_u32_dpp v26, v26, v26 row_bcast:15 row_mask:0xa bank_mask:0xf
	v_max_u32_dpp v27, v27, v27 row_bcast:15 row_mask:0xa bank_mask:0xf
	v_max_u32_dpp v28, v28, v28 row_bcast:15 row_mask:0xa bank_mask:0xf
	v_max_u32_dpp v29, v29, v29 row_bcast:15 row_mask:0xa bank_mask:0xf
	v_max_u32_dpp v26, v26, v26 row_bcast:31 row_mask:0xc bank_mask:0xf
	v_max_u32_dpp v27, v27, v27 row_bcast:31 row_mask:0xc bank_mask:0xf
	v_max_u32_dpp v28, v28, v28 row_bcast:31 row_mask:0xc bank_mask:0xf
	v_max_u32_dpp v29, v29, v29 row_bcast:31 row_mask:0xc bank_mask:0xf
	v_readlane_b32 s14, v26, 63
	v_readlane_b32 s15, v27, 63
	v_readlane_b32 s34, v28, 63
	v_readlane_b32 s35, v29, 63
	v_writelane_b32 v82, s14, 8
	v_writelane_b32 v83, s15, 8
	v_writelane_b32 v84, s34, 8
	v_writelane_b32 v85, s35, 8
	v_cmp_ne_u32_e64 s[42:43], s14, v18
	v_cmp_ne_u32_e64 s[66:67], s14, v22
	v_cmp_ne_u32_e64 s[0:1], s15, v19
	v_cmp_ne_u32_e32 vcc, s15, v23
	v_cndmask_b32_e64 v18, 0, v18, s[42:43]
	v_cndmask_b32_e64 v22, 0, v22, s[66:67]
	v_cndmask_b32_e64 v19, 0, v19, s[0:1]
	v_cndmask_b32_e32 v23, 0, v23, vcc
	v_cmp_ne_u32_e64 s[42:43], s34, v20
	v_cmp_ne_u32_e64 s[66:67], s34, v24
	v_cmp_ne_u32_e64 s[0:1], s35, v21
; __device__ __forceinline__ void nsa_quad_pre(int bg, int quad, const bf16_t* Q, const bf16_t* KV, const bf16_t* KCMP, const bf16_t* VCMPT, const float* GN, bf16_t* ONSA, ...
;     ...
;             for (int it = 0; it < 13; ++it) {
;                 unsigned m = k0 > k1 ? k0 : k1;
; #pragma unroll
;                 for (int off = 32; off >= 1; off >>= 1) { const unsigned o = (unsigned)__shfl_xor((int)m, off); m = o > m ? o : m; }
;                 if (k0 == m) k0 = 0u; if (k1 == m) k1 = 0u;
;                 if (lane == 0) selq[tt * 16 + it] = 127 - (int)(m & 127u);
;             }
	v_cmp_ne_u32_e32 vcc, s35, v25
	v_cndmask_b32_e64 v20, 0, v20, s[42:43]
	v_cndmask_b32_e64 v24, 0, v24, s[66:67]
	v_cndmask_b32_e64 v21, 0, v21, s[0:1]
	v_cndmask_b32_e32 v25, 0, v25, vcc
	v_max_u32_e32 v26, v18, v22
	v_max_u32_e32 v27, v19, v23
	v_max_u32_e32 v28, v20, v24
	v_max_u32_e32 v29, v21, v25
	v_max_u32_dpp v26, v26, v26 quad_perm:[1,0,3,2] row_mask:0xf bank_mask:0xf
	v_max_u32_dpp v27, v27, v27 quad_perm:[1,0,3,2] row_mask:0xf bank_mask:0xf
	v_max_u32_dpp v28, v28, v28 quad_perm:[1,0,3,2] row_mask:0xf bank_mask:0xf
	v_max_u32_dpp v29, v29, v29 quad_perm:[1,0,3,2] row_mask:0xf bank_mask:0xf
	v_max_u32_dpp v26, v26, v26 quad_perm:[2,3,0,1] row_mask:0xf bank_mask:0xf
	v_max_u32_dpp v27, v27, v27 quad_perm:[2,3,0,1] row_mask:0xf bank_mask:0xf
	v_max_u32_dpp v28, v28, v28 quad_perm:[2,3,0,1] row_mask:0xf bank_mask:0xf
	v_max_u32_dpp v29, v29, v29 quad_perm:[2,3,0,1] row_mask:0xf bank_mask:0xf
	v_max_u32_dpp v26, v26, v26 row_half_mirror row_mask:0xf bank_mask:0xf
	v_max_u32_dpp v27, v27, v27 row_half_mirror row_mask:0xf bank_mask:0xf
	v_max_u32_dpp v28, v28, v28 row_half_mirror row_mask:0xf bank_mask:0xf
	v_max_u32_dpp v29, v29, v29 row_half_mirror row_mask:0xf bank_mask:0xf
	v_max_u32_dpp v26, v26, v26 row_mirror row_mask:0xf bank_mask:0xf
	v_max_u32_dpp v27, v27, v27 row_mirror row_mask:0xf bank_mask:0xf
	v_max_u32_dpp v28, v28, v28 row_mirror row_mask:0xf bank_mask:0xf
	v_max_u32_dpp v29, v29, v29 row_mirror row_mask:0xf bank_mask:0xf
	v_max_u32_dpp v26, v26, v26 row_bcast:15 row_mask:0xa bank_mask:0xf
	v_max_u32_dpp v27, v27, v27 row_bcast:15 row_mask:0xa bank_mask:0xf
	v_max_u32_dpp v28, v28, v28 row_bcast:15 row_mask:0xa bank_mask:0xf
	v_max_u32_dpp v29, v29, v29 row_bcast:15 row_mask:0xa bank_mask:0xf
	v_max_u32_dpp v26, v26, v26 row_bcast:31 row_mask:0xc bank_mask:0xf
	v_max_u32_dpp v27, v27, v27 row_bcast:31 row_mask:0xc bank_mask:0xf
	v_max_u32_dpp v28, v28, v28 row_bcast:31 row_mask:0xc bank_mask:0xf
	v_max_u32_dpp v29, v29, v29 row_bcast:31 row_mask:0xc bank_mask:0xf
	v_readlane_b32 s14, v26, 63
	v_readlane_b32 s15, v27, 63
	v_readlane_b32 s34, v28, 63
	v_readlane_b32 s35, v29, 63
	v_writelane_b32 v82, s14, 9
	v_writelane_b32 v83, s15, 9
	v_writelane_b32 v84, s34, 9
	v_writelane_b32 v85, s35, 9
	v_cmp_ne_u32_e64 s[42:43], s14, v18
	v_cmp_ne_u32_e64 s[66:67], s14, v22
	v_cmp_ne_u32_e64 s[0:1], s15, v19
	v_cmp_ne_u32_e32 vcc, s15, v23
	v_cndmask_b32_e64 v18, 0, v18, s[42:43]
	v_cndmask_b32_e64 v22, 0, v22, s[66:67]
	v_cndmask_b32_e64 v19, 0, v19, s[0:1]
	v_cndmask_b32_e32 v23, 0, v23, vcc
	v_cmp_ne_u32_e64 s[42:43], s34, v20
	v_cmp_ne_u32_e64 s[66:67], s34, v24
	v_cmp_ne_u32_e64 s[0:1], s35, v21
	v_cmp_ne_u32_e32 vcc, s35, v25
	v_cndmask_b32_e64 v20, 0, v20, s[42:43]
	v_cndmask_b32_e64 v24, 0, v24, s[66:67]
	v_cndmask_b32_e64 v21, 0, v21, s[0:1]
	v_cndmask_b32_e32 v25, 0, v25, vcc
	v_max_u32_e32 v26, v18, v22
	v_max_u32_e32 v27, v19, v23
	v_max_u32_e32 v28, v20, v24
	v_max_u32_e32 v29, v21, v25
	v_max_u32_dpp v26, v26, v26 quad_perm:[1,0,3,2] row_mask:0xf bank_mask:0xf
	v_max_u32_dpp v27, v27, v27 quad_perm:[1,0,3,2] row_mask:0xf bank_mask:0xf
	v_max_u32_dpp v28, v28, v28 quad_perm:[1,0,3,2] row_mask:0xf bank_mask:0xf
	v_max_u32_dpp v29, v29, v29 quad_perm:[1,0,3,2] row_mask:0xf bank_mask:0xf
	v_max_u32_dpp v26, v26, v26 quad_perm:[2,3,0,1] row_mask:0xf bank_mask:0xf
	v_max_u32_dpp v27, v27, v27 quad_perm:[2,3,0,1] row_mask:0xf bank_mask:0xf
	v_max_u32_dpp v28, v28, v28 quad_perm:[2,3,0,1] row_mask:0xf bank_mask:0xf
	v_max_u32_dpp v29, v29, v29 quad_perm:[2,3,0,1] row_mask:0xf bank_mask:0xf
	v_max_u32_dpp v26, v26, v26 row_half_mirror row_mask:0xf bank_mask:0xf
	v_max_u32_dpp v27, v27, v27 row_half_mirror row_mask:0xf bank_mask:0xf
	v_max_u32_dpp v28, v28, v28 row_half_mirror row_mask:0xf bank_mask:0xf
	v_max_u32_dpp v29, v29, v29 row_half_mirror row_mask:0xf bank_mask:0xf
	v_max_u32_dpp v26, v26, v26 row_mirror row_mask:0xf bank_mask:0xf
	v_max_u32_dpp v27, v27, v27 row_mirror row_mask:0xf bank_mask:0xf
	v_max_u32_dpp v28, v28, v28 row_mirror row_mask:0xf bank_mask:0xf
	v_max_u32_dpp v29, v29, v29 row_mirror row_mask:0xf bank_mask:0xf
	v_max_u32_dpp v26, v26, v26 row_bcast:15 row_mask:0xa bank_mask:0xf
	v_max_u32_dpp v27, v27, v27 row_bcast:15 row_mask:0xa bank_mask:0xf
	v_max_u32_dpp v28, v28, v28 row_bcast:15 row_mask:0xa bank_mask:0xf
	v_max_u32_dpp v29, v29, v29 row_bcast:15 row_mask:0xa bank_mask:0xf
	v_max_u32_dpp v26, v26, v26 row_bcast:31 row_mask:0xc bank_mask:0xf
	v_max_u32_dpp v27, v27, v27 row_bcast:31 row_mask:0xc bank_mask:0xf
	v_max_u32_dpp v28, v28, v28 row_bcast:31 row_mask:0xc bank_mask:0xf
	v_max_u32_dpp v29, v29, v29 row_bcast:31 row_mask:0xc bank_mask:0xf
	v_readlane_b32 s14, v26, 63
	v_readlane_b32 s15, v27, 63
	v_readlane_b32 s34, v28, 63
	v_readlane_b32 s35, v29, 63
	v_writelane_b32 v82, s14, 10
	v_writelane_b32 v83, s15, 10
	v_writelane_b32 v84, s34, 10
	v_writelane_b32 v85, s35, 10
	v_cmp_ne_u32_e64 s[42:43], s14, v18
	v_cmp_ne_u32_e64 s[66:67], s14, v22
	v_cmp_ne_u32_e64 s[0:1], s15, v19
	v_cmp_ne_u32_e32 vcc, s15, v23
	v_cndmask_b32_e64 v18, 0, v18, s[42:43]
	v_cndmask_b32_e64 v22, 0, v22, s[66:67]
	v_cndmask_b32_e64 v19, 0, v19, s[0:1]
	v_cndmask_b32_e32 v23, 0, v23, vcc
	v_cmp_ne_u32_e64 s[42:43], s34, v20
	v_cmp_ne_u32_e64 s[66:67], s34, v24
	v_cmp_ne_u32_e64 s[0:1], s35, v21
	v_cmp_ne_u32_e32 vcc, s35, v25
	v_cndmask_b32_e64 v20, 0, v20, s[42:43]
	v_cndmask_b32_e64 v24, 0, v24, s[66:67]
	v_cndmask_b32_e64 v21, 0, v21, s[0:1]
	v_cndmask_b32_e32 v25, 0, v25, vcc
	v_max_u32_e32 v26, v18, v22
	v_max_u32_e32 v27, v19, v23
	v_max_u32_e32 v28, v20, v24
; __device__ __forceinline__ void nsa_quad_pre(int bg, int quad, const bf16_t* Q, const bf16_t* KV, const bf16_t* KCMP, const bf16_t* VCMPT, const float* GN, bf16_t* ONSA, ...
;     ...
;             for (int it = 0; it < 13; ++it) {
;                 unsigned m = k0 > k1 ? k0 : k1;
; #pragma unroll
;                 for (int off = 32; off >= 1; off >>= 1) { const unsigned o = (unsigned)__shfl_xor((int)m, off); m = o > m ? o : m; }
;                 if (k0 == m) k0 = 0u; if (k1 == m) k1 = 0u;
;                 if (lane == 0) selq[tt * 16 + it] = 127 - (int)(m & 127u);
;             }
;             if (lane == 0) { selq[tt * 16 + 13] = 0; selq[tt * 16 + 14] = cur - 1; selq[tt * 16 + 15] = cur; }
	v_max_u32_e32 v29, v21, v25
	v_max_u32_dpp v26, v26, v26 quad_perm:[1,0,3,2] row_mask:0xf bank_mask:0xf
	v_max_u32_dpp v27, v27, v27 quad_perm:[1,0,3,2] row_mask:0xf bank_mask:0xf
	v_max_u32_dpp v28, v28, v28 quad_perm:[1,0,3,2] row_mask:0xf bank_mask:0xf
	v_max_u32_dpp v29, v29, v29 quad_perm:[1,0,3,2] row_mask:0xf bank_mask:0xf
	v_max_u32_dpp v26, v26, v26 quad_perm:[2,3,0,1] row_mask:0xf bank_mask:0xf
	v_max_u32_dpp v27, v27, v27 quad_perm:[2,3,0,1] row_mask:0xf bank_mask:0xf
	v_max_u32_dpp v28, v28, v28 quad_perm:[2,3,0,1] row_mask:0xf bank_mask:0xf
	v_max_u32_dpp v29, v29, v29 quad_perm:[2,3,0,1] row_mask:0xf bank_mask:0xf
	v_max_u32_dpp v26, v26, v26 row_half_mirror row_mask:0xf bank_mask:0xf
	v_max_u32_dpp v27, v27, v27 row_half_mirror row_mask:0xf bank_mask:0xf
	v_max_u32_dpp v28, v28, v28 row_half_mirror row_mask:0xf bank_mask:0xf
	v_max_u32_dpp v29, v29, v29 row_half_mirror row_mask:0xf bank_mask:0xf
	v_max_u32_dpp v26, v26, v26 row_mirror row_mask:0xf bank_mask:0xf
	v_max_u32_dpp v27, v27, v27 row_mirror row_mask:0xf bank_mask:0xf
	v_max_u32_dpp v28, v28, v28 row_mirror row_mask:0xf bank_mask:0xf
	v_max_u32_dpp v29, v29, v29 row_mirror row_mask:0xf bank_mask:0xf
	v_max_u32_dpp v26, v26, v26 row_bcast:15 row_mask:0xa bank_mask:0xf
	v_max_u32_dpp v27, v27, v27 row_bcast:15 row_mask:0xa bank_mask:0xf
	v_max_u32_dpp v28, v28, v28 row_bcast:15 row_mask:0xa bank_mask:0xf
	v_max_u32_dpp v29, v29, v29 row_bcast:15 row_mask:0xa bank_mask:0xf
	v_max_u32_dpp v26, v26, v26 row_bcast:31 row_mask:0xc bank_mask:0xf
	v_max_u32_dpp v27, v27, v27 row_bcast:31 row_mask:0xc bank_mask:0xf
	v_max_u32_dpp v28, v28, v28 row_bcast:31 row_mask:0xc bank_mask:0xf
	v_max_u32_dpp v29, v29, v29 row_bcast:31 row_mask:0xc bank_mask:0xf
	v_readlane_b32 s14, v26, 63
	v_readlane_b32 s15, v27, 63
	v_readlane_b32 s34, v28, 63
	v_readlane_b32 s35, v29, 63
	v_writelane_b32 v82, s14, 11
	v_writelane_b32 v83, s15, 11
	v_writelane_b32 v84, s34, 11
	v_writelane_b32 v85, s35, 11
	v_cmp_ne_u32_e64 s[42:43], s14, v18
	v_cmp_ne_u32_e64 s[66:67], s14, v22
	v_cmp_ne_u32_e64 s[0:1], s15, v19
	v_cmp_ne_u32_e32 vcc, s15, v23
	v_cndmask_b32_e64 v18, 0, v18, s[42:43]
	v_cndmask_b32_e64 v22, 0, v22, s[66:67]
	v_cndmask_b32_e64 v19, 0, v19, s[0:1]
	v_cndmask_b32_e32 v23, 0, v23, vcc
	v_cmp_ne_u32_e64 s[42:43], s34, v20
	v_cmp_ne_u32_e64 s[66:67], s34, v24
	v_cmp_ne_u32_e64 s[0:1], s35, v21
	v_cmp_ne_u32_e32 vcc, s35, v25
	v_cndmask_b32_e64 v20, 0, v20, s[42:43]
	v_cndmask_b32_e64 v24, 0, v24, s[66:67]
	v_cndmask_b32_e64 v21, 0, v21, s[0:1]
	v_cndmask_b32_e32 v25, 0, v25, vcc
	v_max_u32_e32 v26, v18, v22
	v_max_u32_e32 v27, v19, v23
	v_max_u32_e32 v28, v20, v24
	v_max_u32_e32 v29, v21, v25
	v_max_u32_dpp v26, v26, v26 quad_perm:[1,0,3,2] row_mask:0xf bank_mask:0xf
	v_max_u32_dpp v27, v27, v27 quad_perm:[1,0,3,2] row_mask:0xf bank_mask:0xf
	v_max_u32_dpp v28, v28, v28 quad_perm:[1,0,3,2] row_mask:0xf bank_mask:0xf
	v_max_u32_dpp v29, v29, v29 quad_perm:[1,0,3,2] row_mask:0xf bank_mask:0xf
	v_max_u32_dpp v26, v26, v26 quad_perm:[2,3,0,1] row_mask:0xf bank_mask:0xf
	v_max_u32_dpp v27, v27, v27 quad_perm:[2,3,0,1] row_mask:0xf bank_mask:0xf
	v_max_u32_dpp v28, v28, v28 quad_perm:[2,3,0,1] row_mask:0xf bank_mask:0xf
	v_max_u32_dpp v29, v29, v29 quad_perm:[2,3,0,1] row_mask:0xf bank_mask:0xf
	v_max_u32_dpp v26, v26, v26 row_half_mirror row_mask:0xf bank_mask:0xf
	v_max_u32_dpp v27, v27, v27 row_half_mirror row_mask:0xf bank_mask:0xf
	v_max_u32_dpp v28, v28, v28 row_half_mirror row_mask:0xf bank_mask:0xf
	v_max_u32_dpp v29, v29, v29 row_half_mirror row_mask:0xf bank_mask:0xf
	v_max_u32_dpp v26, v26, v26 row_mirror row_mask:0xf bank_mask:0xf
	v_max_u32_dpp v27, v27, v27 row_mirror row_mask:0xf bank_mask:0xf
	v_max_u32_dpp v28, v28, v28 row_mirror row_mask:0xf bank_mask:0xf
	v_max_u32_dpp v29, v29, v29 row_mirror row_mask:0xf bank_mask:0xf
	v_max_u32_dpp v26, v26, v26 row_bcast:15 row_mask:0xa bank_mask:0xf
	v_max_u32_dpp v27, v27, v27 row_bcast:15 row_mask:0xa bank_mask:0xf
	v_max_u32_dpp v28, v28, v28 row_bcast:15 row_mask:0xa bank_mask:0xf
	v_max_u32_dpp v29, v29, v29 row_bcast:15 row_mask:0xa bank_mask:0xf
	v_max_u32_dpp v26, v26, v26 row_bcast:31 row_mask:0xc bank_mask:0xf
	v_max_u32_dpp v27, v27, v27 row_bcast:31 row_mask:0xc bank_mask:0xf
	v_max_u32_dpp v28, v28, v28 row_bcast:31 row_mask:0xc bank_mask:0xf
	v_max_u32_dpp v29, v29, v29 row_bcast:31 row_mask:0xc bank_mask:0xf
	v_readlane_b32 s14, v26, 63
	v_readlane_b32 s15, v27, 63
	v_readlane_b32 s34, v28, 63
	v_readlane_b32 s35, v29, 63
	v_writelane_b32 v82, s14, 12
	v_writelane_b32 v83, s15, 12
	v_writelane_b32 v84, s34, 12
	v_writelane_b32 v85, s35, 12
	v_and_b32_e32 v82, 127, v82
	v_sub_u32_e32 v82, 127, v82
	v_and_b32_e32 v83, 127, v83
	v_sub_u32_e32 v83, 127, v83
	v_and_b32_e32 v84, 127, v84
	v_sub_u32_e32 v84, 127, v84
	v_and_b32_e32 v85, 127, v85
	v_sub_u32_e32 v85, 127, v85
	s_add_i32 s19, s18, -1
	v_mov_b32_e32 v236, s19
	v_mov_b32_e32 v237, s18
	v_cmp_eq_u32_e64 s[14:15], 14, v184
	v_cmp_eq_u32_e64 s[34:35], 15, v184
	s_nop 0
	v_cndmask_b32_e64 v82, v82, v236, s[14:15]
	v_cndmask_b32_e64 v82, v82, v237, s[34:35]
	v_cndmask_b32_e64 v83, v83, v236, s[14:15]
	v_cndmask_b32_e64 v83, v83, v237, s[34:35]
	v_cndmask_b32_e64 v84, v84, v236, s[14:15]
	v_cndmask_b32_e64 v84, v84, v237, s[34:35]
	v_cndmask_b32_e64 v85, v85, v236, s[14:15]
	v_cndmask_b32_e64 v85, v85, v237, s[34:35]
	s_and_saveexec_b64 s[42:43], s[6:7]
	ds_write_b32 v196, v82 offset:51520
	ds_write_b32 v196, v83 offset:51584
	ds_write_b32 v196, v84 offset:51648
	ds_write_b32 v196, v85 offset:51712
	s_or_b64 exec, exec, s[42:43]
	s_branch .Ltopk_done_q1
